# adaLN GEMV load ring 60 deep instead of 48 (same size, zero displacement); rest = v95
# baseline (speedup 1.0000x reference)
; __device__ __forceinline__ void mod_item(PREF P, int l, int nt, float* sm) {
;     ...
;     const int col = tid & 63, kg = tid >> 6; const float* w = P.w_ada + (size_t)l * DM * 6144 + nt * 64 + col;
;     float a0 = 0.f, a1 = 0.f, a2 = 0.f;
; #pragma unroll 16
;     for (int k = kg * 256; k < kg * 256 + 256; ++k) { const float wv = w[(size_t)k * 6144]; a0 += sc[k] * wv; a1 += sc[2048 + k] * wv; a2 += sc[4096 + k] * wv; }
.LBB0_100:
	v_lshlrev_b32_e32 v184, 2, v1
	s_nop 0
	v_readfirstlane_b32 s52, v4
	v_readfirstlane_b32 s53, v5
	s_nop 4
	global_load_dword v124, v184, s[52:53]
	s_add_u32 s52, s52, 0x6000
	s_addc_u32 s53, s53, 0
	global_load_dword v125, v184, s[52:53]
	s_add_u32 s52, s52, 0x6000
	s_addc_u32 s53, s53, 0
	global_load_dword v126, v184, s[52:53]
	s_add_u32 s52, s52, 0x6000
	s_addc_u32 s53, s53, 0
	global_load_dword v127, v184, s[52:53]
	s_add_u32 s52, s52, 0x6000
	s_addc_u32 s53, s53, 0
	global_load_dword v128, v184, s[52:53]
	s_add_u32 s52, s52, 0x6000
	s_addc_u32 s53, s53, 0
	global_load_dword v129, v184, s[52:53]
	s_add_u32 s52, s52, 0x6000
	s_addc_u32 s53, s53, 0
	global_load_dword v130, v184, s[52:53]
	s_add_u32 s52, s52, 0x6000
	s_addc_u32 s53, s53, 0
	global_load_dword v131, v184, s[52:53]
	s_add_u32 s52, s52, 0x6000
	s_addc_u32 s53, s53, 0
	global_load_dword v132, v184, s[52:53]
	s_add_u32 s52, s52, 0x6000
	s_addc_u32 s53, s53, 0
	global_load_dword v133, v184, s[52:53]
	s_add_u32 s52, s52, 0x6000
	s_addc_u32 s53, s53, 0
	global_load_dword v134, v184, s[52:53]
	s_add_u32 s52, s52, 0x6000
	s_addc_u32 s53, s53, 0
	global_load_dword v135, v184, s[52:53]
	s_add_u32 s52, s52, 0x6000
	s_addc_u32 s53, s53, 0
	global_load_dword v136, v184, s[52:53]
	s_add_u32 s52, s52, 0x6000
	s_addc_u32 s53, s53, 0
	global_load_dword v137, v184, s[52:53]
	s_add_u32 s52, s52, 0x6000
	s_addc_u32 s53, s53, 0
	global_load_dword v138, v184, s[52:53]
	s_add_u32 s52, s52, 0x6000
	s_addc_u32 s53, s53, 0
	global_load_dword v139, v184, s[52:53]
	s_add_u32 s52, s52, 0x6000
	s_addc_u32 s53, s53, 0
	global_load_dword v140, v184, s[52:53]
	s_add_u32 s52, s52, 0x6000
	s_addc_u32 s53, s53, 0
	global_load_dword v141, v184, s[52:53]
	s_add_u32 s52, s52, 0x6000
	s_addc_u32 s53, s53, 0
	global_load_dword v142, v184, s[52:53]
	s_add_u32 s52, s52, 0x6000
	s_addc_u32 s53, s53, 0
	global_load_dword v143, v184, s[52:53]
	s_add_u32 s52, s52, 0x6000
	s_addc_u32 s53, s53, 0
	global_load_dword v144, v184, s[52:53]
	s_add_u32 s52, s52, 0x6000
	s_addc_u32 s53, s53, 0
	global_load_dword v145, v184, s[52:53]
	s_add_u32 s52, s52, 0x6000
	s_addc_u32 s53, s53, 0
	global_load_dword v146, v184, s[52:53]
	s_add_u32 s52, s52, 0x6000
	s_addc_u32 s53, s53, 0
	global_load_dword v147, v184, s[52:53]
	s_add_u32 s52, s52, 0x6000
	s_addc_u32 s53, s53, 0
	global_load_dword v148, v184, s[52:53]
	s_add_u32 s52, s52, 0x6000
	s_addc_u32 s53, s53, 0
	global_load_dword v149, v184, s[52:53]
	s_add_u32 s52, s52, 0x6000
	s_addc_u32 s53, s53, 0
	global_load_dword v150, v184, s[52:53]
	s_add_u32 s52, s52, 0x6000
	s_addc_u32 s53, s53, 0
	global_load_dword v151, v184, s[52:53]
	s_add_u32 s52, s52, 0x6000
	s_addc_u32 s53, s53, 0
	global_load_dword v152, v184, s[52:53]
	s_add_u32 s52, s52, 0x6000
	s_addc_u32 s53, s53, 0
	global_load_dword v153, v184, s[52:53]
	s_add_u32 s52, s52, 0x6000
	s_addc_u32 s53, s53, 0
	global_load_dword v154, v184, s[52:53]
	s_add_u32 s52, s52, 0x6000
	s_addc_u32 s53, s53, 0
	global_load_dword v155, v184, s[52:53]
	s_add_u32 s52, s52, 0x6000
	s_addc_u32 s53, s53, 0
	global_load_dword v156, v184, s[52:53]
	s_add_u32 s52, s52, 0x6000
	s_addc_u32 s53, s53, 0
	global_load_dword v157, v184, s[52:53]
	s_add_u32 s52, s52, 0x6000
	s_addc_u32 s53, s53, 0
	global_load_dword v158, v184, s[52:53]
	s_add_u32 s52, s52, 0x6000
	s_addc_u32 s53, s53, 0
	global_load_dword v159, v184, s[52:53]
	s_add_u32 s52, s52, 0x6000
	s_addc_u32 s53, s53, 0
	global_load_dword v160, v184, s[52:53]
	s_add_u32 s52, s52, 0x6000
	s_addc_u32 s53, s53, 0
	global_load_dword v161, v184, s[52:53]
	s_add_u32 s52, s52, 0x6000
	s_addc_u32 s53, s53, 0
	global_load_dword v162, v184, s[52:53]
	s_add_u32 s52, s52, 0x6000
	s_addc_u32 s53, s53, 0
	global_load_dword v163, v184, s[52:53]
	s_add_u32 s52, s52, 0x6000
	s_addc_u32 s53, s53, 0
	global_load_dword v164, v184, s[52:53]
	s_add_u32 s52, s52, 0x6000
	s_addc_u32 s53, s53, 0
	global_load_dword v165, v184, s[52:53]
	s_add_u32 s52, s52, 0x6000
	s_addc_u32 s53, s53, 0
	global_load_dword v166, v184, s[52:53]
	s_add_u32 s52, s52, 0x6000
	s_addc_u32 s53, s53, 0
	global_load_dword v167, v184, s[52:53]
	s_add_u32 s52, s52, 0x6000
	s_addc_u32 s53, s53, 0
	global_load_dword v168, v184, s[52:53]
	s_add_u32 s52, s52, 0x6000
	s_addc_u32 s53, s53, 0
	global_load_dword v169, v184, s[52:53]
	s_add_u32 s52, s52, 0x6000
	s_addc_u32 s53, s53, 0
	global_load_dword v170, v184, s[52:53]
	s_add_u32 s52, s52, 0x6000
	s_addc_u32 s53, s53, 0
	global_load_dword v171, v184, s[52:53]
	s_add_u32 s52, s52, 0x6000
	s_addc_u32 s53, s53, 0
	global_load_dword v172, v184, s[52:53]
	s_add_u32 s52, s52, 0x6000
	s_addc_u32 s53, s53, 0
	global_load_dword v173, v184, s[52:53]
	s_add_u32 s52, s52, 0x6000
	s_addc_u32 s53, s53, 0
	global_load_dword v174, v184, s[52:53]
	s_add_u32 s52, s52, 0x6000
	s_addc_u32 s53, s53, 0
	global_load_dword v175, v184, s[52:53]
	s_add_u32 s52, s52, 0x6000
	s_addc_u32 s53, s53, 0
	global_load_dword v176, v184, s[52:53]
	s_add_u32 s52, s52, 0x6000
	s_addc_u32 s53, s53, 0
	global_load_dword v177, v184, s[52:53]
	s_add_u32 s52, s52, 0x6000
	s_addc_u32 s53, s53, 0
	global_load_dword v178, v184, s[52:53]
	s_add_u32 s52, s52, 0x6000
	s_addc_u32 s53, s53, 0
	global_load_dword v179, v184, s[52:53]
	s_add_u32 s52, s52, 0x6000
	s_addc_u32 s53, s53, 0
	global_load_dword v180, v184, s[52:53]
	s_add_u32 s52, s52, 0x6000
	s_addc_u32 s53, s53, 0
	global_load_dword v181, v184, s[52:53]
	s_add_u32 s52, s52, 0x6000
	s_addc_u32 s53, s53, 0
	global_load_dword v182, v184, s[52:53]
	s_add_u32 s52, s52, 0x6000
	s_addc_u32 s53, s53, 0
	global_load_dword v183, v184, s[52:53]
	s_add_u32 s52, s52, 0x6000
	s_addc_u32 s53, s53, 0
	ds_read_b128 v[186:189], v12
	ds_read_b128 v[190:193], v12 offset:8192
	ds_read_b128 v[194:197], v12 offset:16384
	ds_read_b128 v[198:201], v12 offset:16
	ds_read_b128 v[202:205], v12 offset:8208
	ds_read_b128 v[206:209], v12 offset:16400
	ds_read_b128 v[210:213], v12 offset:32
	ds_read_b128 v[214:217], v12 offset:8224
	ds_read_b128 v[218:221], v12 offset:16416
	ds_read_b128 v[222:225], v12 offset:48
	ds_read_b128 v[226:229], v12 offset:8240
	ds_read_b128 v[230:233], v12 offset:16432
	s_waitcnt vmcnt(59) lgkmcnt(9)
; __device__ __forceinline__ void mod_item(PREF P, int l, int nt, float* sm) {
;     ...
;     float a0 = 0.f, a1 = 0.f, a2 = 0.f;
; #pragma unroll 16
;     for (int k = kg * 256; k < kg * 256 + 256; ++k) { const float wv = w[(size_t)k * 6144]; a0 += sc[k] * wv; a1 += sc[2048 + k] * wv; a2 += sc[4096 + k] * wv; }
	v_fmac_f32_e32 v6, v124, v186
	v_fmac_f32_e32 v7, v124, v190
	v_fmac_f32_e32 v11, v124, v194
	global_load_dword v124, v184, s[52:53]
	s_add_u32 s52, s52, 0x6000
	s_addc_u32 s53, s53, 0
	s_waitcnt vmcnt(59)
	v_fmac_f32_e32 v6, v125, v187
	v_fmac_f32_e32 v7, v125, v191
	v_fmac_f32_e32 v11, v125, v195
	global_load_dword v125, v184, s[52:53]
	s_add_u32 s52, s52, 0x6000
	s_addc_u32 s53, s53, 0
	s_waitcnt vmcnt(59)
	v_fmac_f32_e32 v6, v126, v188
	v_fmac_f32_e32 v7, v126, v192
	v_fmac_f32_e32 v11, v126, v196
	global_load_dword v126, v184, s[52:53]
	s_add_u32 s52, s52, 0x6000
	s_addc_u32 s53, s53, 0
	s_waitcnt vmcnt(59)
	v_fmac_f32_e32 v6, v127, v189
	v_fmac_f32_e32 v7, v127, v193
	v_fmac_f32_e32 v11, v127, v197
	global_load_dword v127, v184, s[52:53]
	s_add_u32 s52, s52, 0x6000
	s_addc_u32 s53, s53, 0
	ds_read_b128 v[186:189], v12 offset:64
	ds_read_b128 v[190:193], v12 offset:8256
	ds_read_b128 v[194:197], v12 offset:16448
	s_waitcnt vmcnt(59) lgkmcnt(9)
	v_fmac_f32_e32 v6, v128, v198
	v_fmac_f32_e32 v7, v128, v202
	v_fmac_f32_e32 v11, v128, v206
	global_load_dword v128, v184, s[52:53]
	s_add_u32 s52, s52, 0x6000
	s_addc_u32 s53, s53, 0
	s_waitcnt vmcnt(59)
	v_fmac_f32_e32 v6, v129, v199
	v_fmac_f32_e32 v7, v129, v203
	v_fmac_f32_e32 v11, v129, v207
	global_load_dword v129, v184, s[52:53]
	s_add_u32 s52, s52, 0x6000
	s_addc_u32 s53, s53, 0
	s_waitcnt vmcnt(59)
	v_fmac_f32_e32 v6, v130, v200
	v_fmac_f32_e32 v7, v130, v204
	v_fmac_f32_e32 v11, v130, v208
	global_load_dword v130, v184, s[52:53]
	s_add_u32 s52, s52, 0x6000
	s_addc_u32 s53, s53, 0
	s_waitcnt vmcnt(59)
	v_fmac_f32_e32 v6, v131, v201
	v_fmac_f32_e32 v7, v131, v205
	v_fmac_f32_e32 v11, v131, v209
	global_load_dword v131, v184, s[52:53]
	s_add_u32 s52, s52, 0x6000
	s_addc_u32 s53, s53, 0
	ds_read_b128 v[198:201], v12 offset:80
	ds_read_b128 v[202:205], v12 offset:8272
	ds_read_b128 v[206:209], v12 offset:16464
	s_waitcnt vmcnt(59) lgkmcnt(9)
	v_fmac_f32_e32 v6, v132, v210
	v_fmac_f32_e32 v7, v132, v214
	v_fmac_f32_e32 v11, v132, v218
	global_load_dword v132, v184, s[52:53]
	s_add_u32 s52, s52, 0x6000
	s_addc_u32 s53, s53, 0
	s_waitcnt vmcnt(59)
	v_fmac_f32_e32 v6, v133, v211
	v_fmac_f32_e32 v7, v133, v215
	v_fmac_f32_e32 v11, v133, v219
	global_load_dword v133, v184, s[52:53]
	s_add_u32 s52, s52, 0x6000
	s_addc_u32 s53, s53, 0
	s_waitcnt vmcnt(59)
	v_fmac_f32_e32 v6, v134, v212
	v_fmac_f32_e32 v7, v134, v216
	v_fmac_f32_e32 v11, v134, v220
	global_load_dword v134, v184, s[52:53]
	s_add_u32 s52, s52, 0x6000
	s_addc_u32 s53, s53, 0
	s_waitcnt vmcnt(59)
	v_fmac_f32_e32 v6, v135, v213
	v_fmac_f32_e32 v7, v135, v217
	v_fmac_f32_e32 v11, v135, v221
	global_load_dword v135, v184, s[52:53]
	s_add_u32 s52, s52, 0x6000
	s_addc_u32 s53, s53, 0
	ds_read_b128 v[210:213], v12 offset:96
	ds_read_b128 v[214:217], v12 offset:8288
	ds_read_b128 v[218:221], v12 offset:16480
	s_waitcnt vmcnt(59) lgkmcnt(9)
	v_fmac_f32_e32 v6, v136, v222
	v_fmac_f32_e32 v7, v136, v226
	v_fmac_f32_e32 v11, v136, v230
	global_load_dword v136, v184, s[52:53]
	s_add_u32 s52, s52, 0x6000
	s_addc_u32 s53, s53, 0
	s_waitcnt vmcnt(59)
	v_fmac_f32_e32 v6, v137, v223
	v_fmac_f32_e32 v7, v137, v227
	v_fmac_f32_e32 v11, v137, v231
	global_load_dword v137, v184, s[52:53]
	s_add_u32 s52, s52, 0x6000
	s_addc_u32 s53, s53, 0
	s_waitcnt vmcnt(59)
	v_fmac_f32_e32 v6, v138, v224
	v_fmac_f32_e32 v7, v138, v228
	v_fmac_f32_e32 v11, v138, v232
	global_load_dword v138, v184, s[52:53]
	s_add_u32 s52, s52, 0x6000
	s_addc_u32 s53, s53, 0
	s_waitcnt vmcnt(59)
	v_fmac_f32_e32 v6, v139, v225
	v_fmac_f32_e32 v7, v139, v229
	v_fmac_f32_e32 v11, v139, v233
	global_load_dword v139, v184, s[52:53]
	s_add_u32 s52, s52, 0x6000
	s_addc_u32 s53, s53, 0
	ds_read_b128 v[222:225], v12 offset:112
	ds_read_b128 v[226:229], v12 offset:8304
	ds_read_b128 v[230:233], v12 offset:16496
	s_waitcnt vmcnt(59) lgkmcnt(9)
	v_fmac_f32_e32 v6, v140, v186
	v_fmac_f32_e32 v7, v140, v190
	v_fmac_f32_e32 v11, v140, v194
	global_load_dword v140, v184, s[52:53]
	s_add_u32 s52, s52, 0x6000
	s_addc_u32 s53, s53, 0
	s_waitcnt vmcnt(59)
	v_fmac_f32_e32 v6, v141, v187
	v_fmac_f32_e32 v7, v141, v191
	v_fmac_f32_e32 v11, v141, v195
	global_load_dword v141, v184, s[52:53]
	s_add_u32 s52, s52, 0x6000
	s_addc_u32 s53, s53, 0
	s_waitcnt vmcnt(59)
	v_fmac_f32_e32 v6, v142, v188
	v_fmac_f32_e32 v7, v142, v192
	v_fmac_f32_e32 v11, v142, v196
	global_load_dword v142, v184, s[52:53]
	s_add_u32 s52, s52, 0x6000
	s_addc_u32 s53, s53, 0
	s_waitcnt vmcnt(59)
	v_fmac_f32_e32 v6, v143, v189
	v_fmac_f32_e32 v7, v143, v193
	v_fmac_f32_e32 v11, v143, v197
	global_load_dword v143, v184, s[52:53]
	s_add_u32 s52, s52, 0x6000
	s_addc_u32 s53, s53, 0
	ds_read_b128 v[186:189], v12 offset:128
	ds_read_b128 v[190:193], v12 offset:8320
	ds_read_b128 v[194:197], v12 offset:16512
	s_waitcnt vmcnt(59) lgkmcnt(9)
	v_fmac_f32_e32 v6, v144, v198
	v_fmac_f32_e32 v7, v144, v202
	v_fmac_f32_e32 v11, v144, v206
	global_load_dword v144, v184, s[52:53]
	s_add_u32 s52, s52, 0x6000
	s_addc_u32 s53, s53, 0
	s_waitcnt vmcnt(59)
	v_fmac_f32_e32 v6, v145, v199
	v_fmac_f32_e32 v7, v145, v203
	v_fmac_f32_e32 v11, v145, v207
	global_load_dword v145, v184, s[52:53]
	s_add_u32 s52, s52, 0x6000
	s_addc_u32 s53, s53, 0
	s_waitcnt vmcnt(59)
	v_fmac_f32_e32 v6, v146, v200
	v_fmac_f32_e32 v7, v146, v204
	v_fmac_f32_e32 v11, v146, v208
	global_load_dword v146, v184, s[52:53]
	s_add_u32 s52, s52, 0x6000
	s_addc_u32 s53, s53, 0
	s_waitcnt vmcnt(59)
	v_fmac_f32_e32 v6, v147, v201
	v_fmac_f32_e32 v7, v147, v205
	v_fmac_f32_e32 v11, v147, v209
	global_load_dword v147, v184, s[52:53]
	s_add_u32 s52, s52, 0x6000
	s_addc_u32 s53, s53, 0
	ds_read_b128 v[198:201], v12 offset:144
	ds_read_b128 v[202:205], v12 offset:8336
	ds_read_b128 v[206:209], v12 offset:16528
	s_waitcnt vmcnt(59) lgkmcnt(9)
; __device__ __forceinline__ void mod_item(PREF P, int l, int nt, float* sm) {
;     ...
;     float a0 = 0.f, a1 = 0.f, a2 = 0.f;
; #pragma unroll 16
;     for (int k = kg * 256; k < kg * 256 + 256; ++k) { const float wv = w[(size_t)k * 6144]; a0 += sc[k] * wv; a1 += sc[2048 + k] * wv; a2 += sc[4096 + k] * wv; }
	v_fmac_f32_e32 v6, v148, v210
	v_fmac_f32_e32 v7, v148, v214
	v_fmac_f32_e32 v11, v148, v218
	global_load_dword v148, v184, s[52:53]
	s_add_u32 s52, s52, 0x6000
	s_addc_u32 s53, s53, 0
	s_waitcnt vmcnt(59)
	v_fmac_f32_e32 v6, v149, v211
	v_fmac_f32_e32 v7, v149, v215
	v_fmac_f32_e32 v11, v149, v219
	global_load_dword v149, v184, s[52:53]
	s_add_u32 s52, s52, 0x6000
	s_addc_u32 s53, s53, 0
	s_waitcnt vmcnt(59)
	v_fmac_f32_e32 v6, v150, v212
	v_fmac_f32_e32 v7, v150, v216
	v_fmac_f32_e32 v11, v150, v220
	global_load_dword v150, v184, s[52:53]
	s_add_u32 s52, s52, 0x6000
	s_addc_u32 s53, s53, 0
	s_waitcnt vmcnt(59)
	v_fmac_f32_e32 v6, v151, v213
	v_fmac_f32_e32 v7, v151, v217
	v_fmac_f32_e32 v11, v151, v221
	global_load_dword v151, v184, s[52:53]
	s_add_u32 s52, s52, 0x6000
	s_addc_u32 s53, s53, 0
	ds_read_b128 v[210:213], v12 offset:160
	ds_read_b128 v[214:217], v12 offset:8352
	ds_read_b128 v[218:221], v12 offset:16544
	s_waitcnt vmcnt(59) lgkmcnt(9)
	v_fmac_f32_e32 v6, v152, v222
	v_fmac_f32_e32 v7, v152, v226
	v_fmac_f32_e32 v11, v152, v230
	global_load_dword v152, v184, s[52:53]
	s_add_u32 s52, s52, 0x6000
	s_addc_u32 s53, s53, 0
	s_waitcnt vmcnt(59)
	v_fmac_f32_e32 v6, v153, v223
	v_fmac_f32_e32 v7, v153, v227
	v_fmac_f32_e32 v11, v153, v231
	global_load_dword v153, v184, s[52:53]
	s_add_u32 s52, s52, 0x6000
	s_addc_u32 s53, s53, 0
	s_waitcnt vmcnt(59)
	v_fmac_f32_e32 v6, v154, v224
	v_fmac_f32_e32 v7, v154, v228
	v_fmac_f32_e32 v11, v154, v232
	global_load_dword v154, v184, s[52:53]
	s_add_u32 s52, s52, 0x6000
	s_addc_u32 s53, s53, 0
	s_waitcnt vmcnt(59)
	v_fmac_f32_e32 v6, v155, v225
	v_fmac_f32_e32 v7, v155, v229
	v_fmac_f32_e32 v11, v155, v233
	global_load_dword v155, v184, s[52:53]
	s_add_u32 s52, s52, 0x6000
	s_addc_u32 s53, s53, 0
	ds_read_b128 v[222:225], v12 offset:176
	ds_read_b128 v[226:229], v12 offset:8368
	ds_read_b128 v[230:233], v12 offset:16560
	s_waitcnt vmcnt(59) lgkmcnt(9)
	v_fmac_f32_e32 v6, v156, v186
	v_fmac_f32_e32 v7, v156, v190
	v_fmac_f32_e32 v11, v156, v194
	global_load_dword v156, v184, s[52:53]
	s_add_u32 s52, s52, 0x6000
	s_addc_u32 s53, s53, 0
	s_waitcnt vmcnt(59)
	v_fmac_f32_e32 v6, v157, v187
	v_fmac_f32_e32 v7, v157, v191
	v_fmac_f32_e32 v11, v157, v195
	global_load_dword v157, v184, s[52:53]
	s_add_u32 s52, s52, 0x6000
	s_addc_u32 s53, s53, 0
	s_waitcnt vmcnt(59)
	v_fmac_f32_e32 v6, v158, v188
	v_fmac_f32_e32 v7, v158, v192
	v_fmac_f32_e32 v11, v158, v196
	global_load_dword v158, v184, s[52:53]
	s_add_u32 s52, s52, 0x6000
	s_addc_u32 s53, s53, 0
	s_waitcnt vmcnt(59)
	v_fmac_f32_e32 v6, v159, v189
	v_fmac_f32_e32 v7, v159, v193
	v_fmac_f32_e32 v11, v159, v197
	global_load_dword v159, v184, s[52:53]
	s_add_u32 s52, s52, 0x6000
	s_addc_u32 s53, s53, 0
	ds_read_b128 v[186:189], v12 offset:192
	ds_read_b128 v[190:193], v12 offset:8384
	ds_read_b128 v[194:197], v12 offset:16576
	s_waitcnt vmcnt(59) lgkmcnt(9)
	v_fmac_f32_e32 v6, v160, v198
	v_fmac_f32_e32 v7, v160, v202
	v_fmac_f32_e32 v11, v160, v206
	global_load_dword v160, v184, s[52:53]
	s_add_u32 s52, s52, 0x6000
	s_addc_u32 s53, s53, 0
	s_waitcnt vmcnt(59)
	v_fmac_f32_e32 v6, v161, v199
	v_fmac_f32_e32 v7, v161, v203
	v_fmac_f32_e32 v11, v161, v207
	global_load_dword v161, v184, s[52:53]
	s_add_u32 s52, s52, 0x6000
	s_addc_u32 s53, s53, 0
	s_waitcnt vmcnt(59)
	v_fmac_f32_e32 v6, v162, v200
	v_fmac_f32_e32 v7, v162, v204
	v_fmac_f32_e32 v11, v162, v208
	global_load_dword v162, v184, s[52:53]
	s_add_u32 s52, s52, 0x6000
	s_addc_u32 s53, s53, 0
	s_waitcnt vmcnt(59)
	v_fmac_f32_e32 v6, v163, v201
	v_fmac_f32_e32 v7, v163, v205
	v_fmac_f32_e32 v11, v163, v209
	global_load_dword v163, v184, s[52:53]
	s_add_u32 s52, s52, 0x6000
	s_addc_u32 s53, s53, 0
	ds_read_b128 v[198:201], v12 offset:208
	ds_read_b128 v[202:205], v12 offset:8400
	ds_read_b128 v[206:209], v12 offset:16592
	s_waitcnt vmcnt(59) lgkmcnt(9)
	v_fmac_f32_e32 v6, v164, v210
	v_fmac_f32_e32 v7, v164, v214
	v_fmac_f32_e32 v11, v164, v218
	global_load_dword v164, v184, s[52:53]
	s_add_u32 s52, s52, 0x6000
	s_addc_u32 s53, s53, 0
	s_waitcnt vmcnt(59)
	v_fmac_f32_e32 v6, v165, v211
	v_fmac_f32_e32 v7, v165, v215
	v_fmac_f32_e32 v11, v165, v219
	global_load_dword v165, v184, s[52:53]
	s_add_u32 s52, s52, 0x6000
	s_addc_u32 s53, s53, 0
	s_waitcnt vmcnt(59)
	v_fmac_f32_e32 v6, v166, v212
	v_fmac_f32_e32 v7, v166, v216
	v_fmac_f32_e32 v11, v166, v220
	global_load_dword v166, v184, s[52:53]
	s_add_u32 s52, s52, 0x6000
	s_addc_u32 s53, s53, 0
	s_waitcnt vmcnt(59)
	v_fmac_f32_e32 v6, v167, v213
	v_fmac_f32_e32 v7, v167, v217
	v_fmac_f32_e32 v11, v167, v221
	global_load_dword v167, v184, s[52:53]
	s_add_u32 s52, s52, 0x6000
	s_addc_u32 s53, s53, 0
	ds_read_b128 v[210:213], v12 offset:224
	ds_read_b128 v[214:217], v12 offset:8416
	ds_read_b128 v[218:221], v12 offset:16608
	s_waitcnt vmcnt(59) lgkmcnt(9)
	v_fmac_f32_e32 v6, v168, v222
	v_fmac_f32_e32 v7, v168, v226
	v_fmac_f32_e32 v11, v168, v230
	global_load_dword v168, v184, s[52:53]
	s_add_u32 s52, s52, 0x6000
	s_addc_u32 s53, s53, 0
	s_waitcnt vmcnt(59)
	v_fmac_f32_e32 v6, v169, v223
	v_fmac_f32_e32 v7, v169, v227
	v_fmac_f32_e32 v11, v169, v231
	global_load_dword v169, v184, s[52:53]
	s_add_u32 s52, s52, 0x6000
	s_addc_u32 s53, s53, 0
	s_waitcnt vmcnt(59)
	v_fmac_f32_e32 v6, v170, v224
	v_fmac_f32_e32 v7, v170, v228
	v_fmac_f32_e32 v11, v170, v232
	global_load_dword v170, v184, s[52:53]
	s_add_u32 s52, s52, 0x6000
	s_addc_u32 s53, s53, 0
	s_waitcnt vmcnt(59)
	v_fmac_f32_e32 v6, v171, v225
	v_fmac_f32_e32 v7, v171, v229
	v_fmac_f32_e32 v11, v171, v233
	global_load_dword v171, v184, s[52:53]
	s_add_u32 s52, s52, 0x6000
	s_addc_u32 s53, s53, 0
	ds_read_b128 v[222:225], v12 offset:240
	ds_read_b128 v[226:229], v12 offset:8432
	ds_read_b128 v[230:233], v12 offset:16624
	s_waitcnt vmcnt(59) lgkmcnt(9)
; __device__ __forceinline__ void mod_item(PREF P, int l, int nt, float* sm) {
;     ...
;     float a0 = 0.f, a1 = 0.f, a2 = 0.f;
; #pragma unroll 16
;     for (int k = kg * 256; k < kg * 256 + 256; ++k) { const float wv = w[(size_t)k * 6144]; a0 += sc[k] * wv; a1 += sc[2048 + k] * wv; a2 += sc[4096 + k] * wv; }
	v_fmac_f32_e32 v6, v172, v186
	v_fmac_f32_e32 v7, v172, v190
	v_fmac_f32_e32 v11, v172, v194
	global_load_dword v172, v184, s[52:53]
	s_add_u32 s52, s52, 0x6000
	s_addc_u32 s53, s53, 0
	s_waitcnt vmcnt(59)
	v_fmac_f32_e32 v6, v173, v187
	v_fmac_f32_e32 v7, v173, v191
	v_fmac_f32_e32 v11, v173, v195
	global_load_dword v173, v184, s[52:53]
	s_add_u32 s52, s52, 0x6000
	s_addc_u32 s53, s53, 0
	s_waitcnt vmcnt(59)
	v_fmac_f32_e32 v6, v174, v188
	v_fmac_f32_e32 v7, v174, v192
	v_fmac_f32_e32 v11, v174, v196
	global_load_dword v174, v184, s[52:53]
	s_add_u32 s52, s52, 0x6000
	s_addc_u32 s53, s53, 0
	s_waitcnt vmcnt(59)
	v_fmac_f32_e32 v6, v175, v189
	v_fmac_f32_e32 v7, v175, v193
	v_fmac_f32_e32 v11, v175, v197
	global_load_dword v175, v184, s[52:53]
	s_add_u32 s52, s52, 0x6000
	s_addc_u32 s53, s53, 0
	ds_read_b128 v[186:189], v12 offset:256
	ds_read_b128 v[190:193], v12 offset:8448
	ds_read_b128 v[194:197], v12 offset:16640
	s_waitcnt vmcnt(59) lgkmcnt(9)
	v_fmac_f32_e32 v6, v176, v198
	v_fmac_f32_e32 v7, v176, v202
	v_fmac_f32_e32 v11, v176, v206
	global_load_dword v176, v184, s[52:53]
	s_add_u32 s52, s52, 0x6000
	s_addc_u32 s53, s53, 0
	s_waitcnt vmcnt(59)
	v_fmac_f32_e32 v6, v177, v199
	v_fmac_f32_e32 v7, v177, v203
	v_fmac_f32_e32 v11, v177, v207
	global_load_dword v177, v184, s[52:53]
	s_add_u32 s52, s52, 0x6000
	s_addc_u32 s53, s53, 0
	s_waitcnt vmcnt(59)
	v_fmac_f32_e32 v6, v178, v200
	v_fmac_f32_e32 v7, v178, v204
	v_fmac_f32_e32 v11, v178, v208
	global_load_dword v178, v184, s[52:53]
	s_add_u32 s52, s52, 0x6000
	s_addc_u32 s53, s53, 0
	s_waitcnt vmcnt(59)
	v_fmac_f32_e32 v6, v179, v201
	v_fmac_f32_e32 v7, v179, v205
	v_fmac_f32_e32 v11, v179, v209
	global_load_dword v179, v184, s[52:53]
	s_add_u32 s52, s52, 0x6000
	s_addc_u32 s53, s53, 0
	ds_read_b128 v[198:201], v12 offset:272
	ds_read_b128 v[202:205], v12 offset:8464
	ds_read_b128 v[206:209], v12 offset:16656
	s_waitcnt vmcnt(59) lgkmcnt(9)
	v_fmac_f32_e32 v6, v180, v210
	v_fmac_f32_e32 v7, v180, v214
	v_fmac_f32_e32 v11, v180, v218
	global_load_dword v180, v184, s[52:53]
	s_add_u32 s52, s52, 0x6000
	s_addc_u32 s53, s53, 0
	s_waitcnt vmcnt(59)
	v_fmac_f32_e32 v6, v181, v211
	v_fmac_f32_e32 v7, v181, v215
	v_fmac_f32_e32 v11, v181, v219
	global_load_dword v181, v184, s[52:53]
	s_add_u32 s52, s52, 0x6000
	s_addc_u32 s53, s53, 0
	s_waitcnt vmcnt(59)
	v_fmac_f32_e32 v6, v182, v212
	v_fmac_f32_e32 v7, v182, v216
	v_fmac_f32_e32 v11, v182, v220
	global_load_dword v182, v184, s[52:53]
	s_add_u32 s52, s52, 0x6000
	s_addc_u32 s53, s53, 0
	s_waitcnt vmcnt(59)
	v_fmac_f32_e32 v6, v183, v213
	v_fmac_f32_e32 v7, v183, v217
	v_fmac_f32_e32 v11, v183, v221
	global_load_dword v183, v184, s[52:53]
	s_add_u32 s52, s52, 0x6000
	s_addc_u32 s53, s53, 0
	ds_read_b128 v[210:213], v12 offset:288
	ds_read_b128 v[214:217], v12 offset:8480
	ds_read_b128 v[218:221], v12 offset:16672
	s_waitcnt vmcnt(59) lgkmcnt(9)
	v_fmac_f32_e32 v6, v124, v222
	v_fmac_f32_e32 v7, v124, v226
	v_fmac_f32_e32 v11, v124, v230
	global_load_dword v124, v184, s[52:53]
	s_add_u32 s52, s52, 0x6000
	s_addc_u32 s53, s53, 0
	s_waitcnt vmcnt(59)
	v_fmac_f32_e32 v6, v125, v223
	v_fmac_f32_e32 v7, v125, v227
	v_fmac_f32_e32 v11, v125, v231
	global_load_dword v125, v184, s[52:53]
	s_add_u32 s52, s52, 0x6000
	s_addc_u32 s53, s53, 0
	s_waitcnt vmcnt(59)
	v_fmac_f32_e32 v6, v126, v224
	v_fmac_f32_e32 v7, v126, v228
	v_fmac_f32_e32 v11, v126, v232
	global_load_dword v126, v184, s[52:53]
	s_add_u32 s52, s52, 0x6000
	s_addc_u32 s53, s53, 0
	s_waitcnt vmcnt(59)
	v_fmac_f32_e32 v6, v127, v225
	v_fmac_f32_e32 v7, v127, v229
	v_fmac_f32_e32 v11, v127, v233
	global_load_dword v127, v184, s[52:53]
	s_add_u32 s52, s52, 0x6000
	s_addc_u32 s53, s53, 0
	ds_read_b128 v[222:225], v12 offset:304
	ds_read_b128 v[226:229], v12 offset:8496
	ds_read_b128 v[230:233], v12 offset:16688
	s_waitcnt vmcnt(59) lgkmcnt(9)
	v_fmac_f32_e32 v6, v128, v186
	v_fmac_f32_e32 v7, v128, v190
	v_fmac_f32_e32 v11, v128, v194
	global_load_dword v128, v184, s[52:53]
	s_add_u32 s52, s52, 0x6000
	s_addc_u32 s53, s53, 0
	s_waitcnt vmcnt(59)
	v_fmac_f32_e32 v6, v129, v187
	v_fmac_f32_e32 v7, v129, v191
	v_fmac_f32_e32 v11, v129, v195
	global_load_dword v129, v184, s[52:53]
	s_add_u32 s52, s52, 0x6000
	s_addc_u32 s53, s53, 0
	s_waitcnt vmcnt(59)
	v_fmac_f32_e32 v6, v130, v188
	v_fmac_f32_e32 v7, v130, v192
	v_fmac_f32_e32 v11, v130, v196
	global_load_dword v130, v184, s[52:53]
	s_add_u32 s52, s52, 0x6000
	s_addc_u32 s53, s53, 0
	s_waitcnt vmcnt(59)
	v_fmac_f32_e32 v6, v131, v189
	v_fmac_f32_e32 v7, v131, v193
	v_fmac_f32_e32 v11, v131, v197
	global_load_dword v131, v184, s[52:53]
	s_add_u32 s52, s52, 0x6000
	s_addc_u32 s53, s53, 0
	ds_read_b128 v[186:189], v12 offset:320
	ds_read_b128 v[190:193], v12 offset:8512
	ds_read_b128 v[194:197], v12 offset:16704
	s_waitcnt vmcnt(59) lgkmcnt(9)
	v_fmac_f32_e32 v6, v132, v198
	v_fmac_f32_e32 v7, v132, v202
	v_fmac_f32_e32 v11, v132, v206
	global_load_dword v132, v184, s[52:53]
	s_add_u32 s52, s52, 0x6000
	s_addc_u32 s53, s53, 0
	s_waitcnt vmcnt(59)
	v_fmac_f32_e32 v6, v133, v199
	v_fmac_f32_e32 v7, v133, v203
	v_fmac_f32_e32 v11, v133, v207
	global_load_dword v133, v184, s[52:53]
	s_add_u32 s52, s52, 0x6000
	s_addc_u32 s53, s53, 0
	s_waitcnt vmcnt(59)
	v_fmac_f32_e32 v6, v134, v200
	v_fmac_f32_e32 v7, v134, v204
	v_fmac_f32_e32 v11, v134, v208
	global_load_dword v134, v184, s[52:53]
	s_add_u32 s52, s52, 0x6000
	s_addc_u32 s53, s53, 0
	s_waitcnt vmcnt(59)
	v_fmac_f32_e32 v6, v135, v201
	v_fmac_f32_e32 v7, v135, v205
	v_fmac_f32_e32 v11, v135, v209
	global_load_dword v135, v184, s[52:53]
	s_add_u32 s52, s52, 0x6000
	s_addc_u32 s53, s53, 0
	ds_read_b128 v[198:201], v12 offset:336
	ds_read_b128 v[202:205], v12 offset:8528
	ds_read_b128 v[206:209], v12 offset:16720
	s_waitcnt vmcnt(59) lgkmcnt(9)
; __device__ __forceinline__ void mod_item(PREF P, int l, int nt, float* sm) {
;     ...
;     float a0 = 0.f, a1 = 0.f, a2 = 0.f;
; #pragma unroll 16
;     for (int k = kg * 256; k < kg * 256 + 256; ++k) { const float wv = w[(size_t)k * 6144]; a0 += sc[k] * wv; a1 += sc[2048 + k] * wv; a2 += sc[4096 + k] * wv; }
	v_fmac_f32_e32 v6, v136, v210
	v_fmac_f32_e32 v7, v136, v214
	v_fmac_f32_e32 v11, v136, v218
	global_load_dword v136, v184, s[52:53]
	s_add_u32 s52, s52, 0x6000
	s_addc_u32 s53, s53, 0
	s_waitcnt vmcnt(59)
	v_fmac_f32_e32 v6, v137, v211
	v_fmac_f32_e32 v7, v137, v215
	v_fmac_f32_e32 v11, v137, v219
	global_load_dword v137, v184, s[52:53]
	s_add_u32 s52, s52, 0x6000
	s_addc_u32 s53, s53, 0
	s_waitcnt vmcnt(59)
	v_fmac_f32_e32 v6, v138, v212
	v_fmac_f32_e32 v7, v138, v216
	v_fmac_f32_e32 v11, v138, v220
	global_load_dword v138, v184, s[52:53]
	s_add_u32 s52, s52, 0x6000
	s_addc_u32 s53, s53, 0
	s_waitcnt vmcnt(59)
	v_fmac_f32_e32 v6, v139, v213
	v_fmac_f32_e32 v7, v139, v217
	v_fmac_f32_e32 v11, v139, v221
	global_load_dword v139, v184, s[52:53]
	s_add_u32 s52, s52, 0x6000
	s_addc_u32 s53, s53, 0
	ds_read_b128 v[210:213], v12 offset:352
	ds_read_b128 v[214:217], v12 offset:8544
	ds_read_b128 v[218:221], v12 offset:16736
	s_waitcnt vmcnt(59) lgkmcnt(9)
	v_fmac_f32_e32 v6, v140, v222
	v_fmac_f32_e32 v7, v140, v226
	v_fmac_f32_e32 v11, v140, v230
	global_load_dword v140, v184, s[52:53]
	s_add_u32 s52, s52, 0x6000
	s_addc_u32 s53, s53, 0
	s_waitcnt vmcnt(59)
	v_fmac_f32_e32 v6, v141, v223
	v_fmac_f32_e32 v7, v141, v227
	v_fmac_f32_e32 v11, v141, v231
	global_load_dword v141, v184, s[52:53]
	s_add_u32 s52, s52, 0x6000
	s_addc_u32 s53, s53, 0
	s_waitcnt vmcnt(59)
	v_fmac_f32_e32 v6, v142, v224
	v_fmac_f32_e32 v7, v142, v228
	v_fmac_f32_e32 v11, v142, v232
	global_load_dword v142, v184, s[52:53]
	s_add_u32 s52, s52, 0x6000
	s_addc_u32 s53, s53, 0
	s_waitcnt vmcnt(59)
	v_fmac_f32_e32 v6, v143, v225
	v_fmac_f32_e32 v7, v143, v229
	v_fmac_f32_e32 v11, v143, v233
	global_load_dword v143, v184, s[52:53]
	s_add_u32 s52, s52, 0x6000
	s_addc_u32 s53, s53, 0
	ds_read_b128 v[222:225], v12 offset:368
	ds_read_b128 v[226:229], v12 offset:8560
	ds_read_b128 v[230:233], v12 offset:16752
	s_waitcnt vmcnt(59) lgkmcnt(9)
	v_fmac_f32_e32 v6, v144, v186
	v_fmac_f32_e32 v7, v144, v190
	v_fmac_f32_e32 v11, v144, v194
	global_load_dword v144, v184, s[52:53]
	s_add_u32 s52, s52, 0x6000
	s_addc_u32 s53, s53, 0
	s_waitcnt vmcnt(59)
	v_fmac_f32_e32 v6, v145, v187
	v_fmac_f32_e32 v7, v145, v191
	v_fmac_f32_e32 v11, v145, v195
	global_load_dword v145, v184, s[52:53]
	s_add_u32 s52, s52, 0x6000
	s_addc_u32 s53, s53, 0
	s_waitcnt vmcnt(59)
	v_fmac_f32_e32 v6, v146, v188
	v_fmac_f32_e32 v7, v146, v192
	v_fmac_f32_e32 v11, v146, v196
	global_load_dword v146, v184, s[52:53]
	s_add_u32 s52, s52, 0x6000
	s_addc_u32 s53, s53, 0
	s_waitcnt vmcnt(59)
	v_fmac_f32_e32 v6, v147, v189
	v_fmac_f32_e32 v7, v147, v193
	v_fmac_f32_e32 v11, v147, v197
	global_load_dword v147, v184, s[52:53]
	s_add_u32 s52, s52, 0x6000
	s_addc_u32 s53, s53, 0
	ds_read_b128 v[186:189], v12 offset:384
	ds_read_b128 v[190:193], v12 offset:8576
	ds_read_b128 v[194:197], v12 offset:16768
	s_waitcnt vmcnt(59) lgkmcnt(9)
	v_fmac_f32_e32 v6, v148, v198
	v_fmac_f32_e32 v7, v148, v202
	v_fmac_f32_e32 v11, v148, v206
	global_load_dword v148, v184, s[52:53]
	s_add_u32 s52, s52, 0x6000
	s_addc_u32 s53, s53, 0
	s_waitcnt vmcnt(59)
	v_fmac_f32_e32 v6, v149, v199
	v_fmac_f32_e32 v7, v149, v203
	v_fmac_f32_e32 v11, v149, v207
	global_load_dword v149, v184, s[52:53]
	s_add_u32 s52, s52, 0x6000
	s_addc_u32 s53, s53, 0
	s_waitcnt vmcnt(59)
	v_fmac_f32_e32 v6, v150, v200
	v_fmac_f32_e32 v7, v150, v204
	v_fmac_f32_e32 v11, v150, v208
	global_load_dword v150, v184, s[52:53]
	s_add_u32 s52, s52, 0x6000
	s_addc_u32 s53, s53, 0
	s_waitcnt vmcnt(59)
	v_fmac_f32_e32 v6, v151, v201
	v_fmac_f32_e32 v7, v151, v205
	v_fmac_f32_e32 v11, v151, v209
	global_load_dword v151, v184, s[52:53]
	s_add_u32 s52, s52, 0x6000
	s_addc_u32 s53, s53, 0
	ds_read_b128 v[198:201], v12 offset:400
	ds_read_b128 v[202:205], v12 offset:8592
	ds_read_b128 v[206:209], v12 offset:16784
	s_waitcnt vmcnt(59) lgkmcnt(9)
	v_fmac_f32_e32 v6, v152, v210
	v_fmac_f32_e32 v7, v152, v214
	v_fmac_f32_e32 v11, v152, v218
	global_load_dword v152, v184, s[52:53]
	s_add_u32 s52, s52, 0x6000
	s_addc_u32 s53, s53, 0
	s_waitcnt vmcnt(59)
	v_fmac_f32_e32 v6, v153, v211
	v_fmac_f32_e32 v7, v153, v215
	v_fmac_f32_e32 v11, v153, v219
	global_load_dword v153, v184, s[52:53]
	s_add_u32 s52, s52, 0x6000
	s_addc_u32 s53, s53, 0
	s_waitcnt vmcnt(59)
	v_fmac_f32_e32 v6, v154, v212
	v_fmac_f32_e32 v7, v154, v216
	v_fmac_f32_e32 v11, v154, v220
	global_load_dword v154, v184, s[52:53]
	s_add_u32 s52, s52, 0x6000
	s_addc_u32 s53, s53, 0
	s_waitcnt vmcnt(59)
	v_fmac_f32_e32 v6, v155, v213
	v_fmac_f32_e32 v7, v155, v217
	v_fmac_f32_e32 v11, v155, v221
	global_load_dword v155, v184, s[52:53]
	s_add_u32 s52, s52, 0x6000
	s_addc_u32 s53, s53, 0
	ds_read_b128 v[210:213], v12 offset:416
	ds_read_b128 v[214:217], v12 offset:8608
	ds_read_b128 v[218:221], v12 offset:16800
	s_waitcnt vmcnt(59) lgkmcnt(9)
	v_fmac_f32_e32 v6, v156, v222
	v_fmac_f32_e32 v7, v156, v226
	v_fmac_f32_e32 v11, v156, v230
	global_load_dword v156, v184, s[52:53]
	s_add_u32 s52, s52, 0x6000
	s_addc_u32 s53, s53, 0
	s_waitcnt vmcnt(59)
	v_fmac_f32_e32 v6, v157, v223
	v_fmac_f32_e32 v7, v157, v227
	v_fmac_f32_e32 v11, v157, v231
	global_load_dword v157, v184, s[52:53]
	s_add_u32 s52, s52, 0x6000
	s_addc_u32 s53, s53, 0
	s_waitcnt vmcnt(59)
	v_fmac_f32_e32 v6, v158, v224
	v_fmac_f32_e32 v7, v158, v228
	v_fmac_f32_e32 v11, v158, v232
	global_load_dword v158, v184, s[52:53]
	s_add_u32 s52, s52, 0x6000
	s_addc_u32 s53, s53, 0
	s_waitcnt vmcnt(59)
	v_fmac_f32_e32 v6, v159, v225
	v_fmac_f32_e32 v7, v159, v229
	v_fmac_f32_e32 v11, v159, v233
	global_load_dword v159, v184, s[52:53]
	s_add_u32 s52, s52, 0x6000
	s_addc_u32 s53, s53, 0
	ds_read_b128 v[222:225], v12 offset:432
	ds_read_b128 v[226:229], v12 offset:8624
	ds_read_b128 v[230:233], v12 offset:16816
	s_waitcnt vmcnt(59) lgkmcnt(9)
; __device__ __forceinline__ void mod_item(PREF P, int l, int nt, float* sm) {
;     ...
;     float a0 = 0.f, a1 = 0.f, a2 = 0.f;
; #pragma unroll 16
;     for (int k = kg * 256; k < kg * 256 + 256; ++k) { const float wv = w[(size_t)k * 6144]; a0 += sc[k] * wv; a1 += sc[2048 + k] * wv; a2 += sc[4096 + k] * wv; }
	v_fmac_f32_e32 v6, v160, v186
	v_fmac_f32_e32 v7, v160, v190
	v_fmac_f32_e32 v11, v160, v194
	global_load_dword v160, v184, s[52:53]
	s_add_u32 s52, s52, 0x6000
	s_addc_u32 s53, s53, 0
	s_waitcnt vmcnt(59)
	v_fmac_f32_e32 v6, v161, v187
	v_fmac_f32_e32 v7, v161, v191
	v_fmac_f32_e32 v11, v161, v195
	global_load_dword v161, v184, s[52:53]
	s_add_u32 s52, s52, 0x6000
	s_addc_u32 s53, s53, 0
	s_waitcnt vmcnt(59)
	v_fmac_f32_e32 v6, v162, v188
	v_fmac_f32_e32 v7, v162, v192
	v_fmac_f32_e32 v11, v162, v196
	global_load_dword v162, v184, s[52:53]
	s_add_u32 s52, s52, 0x6000
	s_addc_u32 s53, s53, 0
	s_waitcnt vmcnt(59)
	v_fmac_f32_e32 v6, v163, v189
	v_fmac_f32_e32 v7, v163, v193
	v_fmac_f32_e32 v11, v163, v197
	global_load_dword v163, v184, s[52:53]
	s_add_u32 s52, s52, 0x6000
	s_addc_u32 s53, s53, 0
	ds_read_b128 v[186:189], v12 offset:448
	ds_read_b128 v[190:193], v12 offset:8640
	ds_read_b128 v[194:197], v12 offset:16832
	s_waitcnt vmcnt(59) lgkmcnt(9)
	v_fmac_f32_e32 v6, v164, v198
	v_fmac_f32_e32 v7, v164, v202
	v_fmac_f32_e32 v11, v164, v206
	global_load_dword v164, v184, s[52:53]
	s_add_u32 s52, s52, 0x6000
	s_addc_u32 s53, s53, 0
	s_waitcnt vmcnt(59)
	v_fmac_f32_e32 v6, v165, v199
	v_fmac_f32_e32 v7, v165, v203
	v_fmac_f32_e32 v11, v165, v207
	global_load_dword v165, v184, s[52:53]
	s_add_u32 s52, s52, 0x6000
	s_addc_u32 s53, s53, 0
	s_waitcnt vmcnt(59)
	v_fmac_f32_e32 v6, v166, v200
	v_fmac_f32_e32 v7, v166, v204
	v_fmac_f32_e32 v11, v166, v208
	global_load_dword v166, v184, s[52:53]
	s_add_u32 s52, s52, 0x6000
	s_addc_u32 s53, s53, 0
	s_waitcnt vmcnt(59)
	v_fmac_f32_e32 v6, v167, v201
	v_fmac_f32_e32 v7, v167, v205
	v_fmac_f32_e32 v11, v167, v209
	global_load_dword v167, v184, s[52:53]
	s_add_u32 s52, s52, 0x6000
	s_addc_u32 s53, s53, 0
	ds_read_b128 v[198:201], v12 offset:464
	ds_read_b128 v[202:205], v12 offset:8656
	ds_read_b128 v[206:209], v12 offset:16848
	s_waitcnt vmcnt(59) lgkmcnt(9)
	v_fmac_f32_e32 v6, v168, v210
	v_fmac_f32_e32 v7, v168, v214
	v_fmac_f32_e32 v11, v168, v218
	global_load_dword v168, v184, s[52:53]
	s_add_u32 s52, s52, 0x6000
	s_addc_u32 s53, s53, 0
	s_waitcnt vmcnt(59)
	v_fmac_f32_e32 v6, v169, v211
	v_fmac_f32_e32 v7, v169, v215
	v_fmac_f32_e32 v11, v169, v219
	global_load_dword v169, v184, s[52:53]
	s_add_u32 s52, s52, 0x6000
	s_addc_u32 s53, s53, 0
	s_waitcnt vmcnt(59)
	v_fmac_f32_e32 v6, v170, v212
	v_fmac_f32_e32 v7, v170, v216
	v_fmac_f32_e32 v11, v170, v220
	global_load_dword v170, v184, s[52:53]
	s_add_u32 s52, s52, 0x6000
	s_addc_u32 s53, s53, 0
	s_waitcnt vmcnt(59)
	v_fmac_f32_e32 v6, v171, v213
	v_fmac_f32_e32 v7, v171, v217
	v_fmac_f32_e32 v11, v171, v221
	global_load_dword v171, v184, s[52:53]
	s_add_u32 s52, s52, 0x6000
	s_addc_u32 s53, s53, 0
	ds_read_b128 v[210:213], v12 offset:480
	ds_read_b128 v[214:217], v12 offset:8672
	ds_read_b128 v[218:221], v12 offset:16864
	s_waitcnt vmcnt(59) lgkmcnt(9)
	v_fmac_f32_e32 v6, v172, v222
	v_fmac_f32_e32 v7, v172, v226
	v_fmac_f32_e32 v11, v172, v230
	global_load_dword v172, v184, s[52:53]
	s_add_u32 s52, s52, 0x6000
	s_addc_u32 s53, s53, 0
	s_waitcnt vmcnt(59)
	v_fmac_f32_e32 v6, v173, v223
	v_fmac_f32_e32 v7, v173, v227
	v_fmac_f32_e32 v11, v173, v231
	global_load_dword v173, v184, s[52:53]
	s_add_u32 s52, s52, 0x6000
	s_addc_u32 s53, s53, 0
	s_waitcnt vmcnt(59)
	v_fmac_f32_e32 v6, v174, v224
	v_fmac_f32_e32 v7, v174, v228
	v_fmac_f32_e32 v11, v174, v232
	global_load_dword v174, v184, s[52:53]
	s_add_u32 s52, s52, 0x6000
	s_addc_u32 s53, s53, 0
	s_waitcnt vmcnt(59)
	v_fmac_f32_e32 v6, v175, v225
	v_fmac_f32_e32 v7, v175, v229
	v_fmac_f32_e32 v11, v175, v233
	global_load_dword v175, v184, s[52:53]
	s_add_u32 s52, s52, 0x6000
	s_addc_u32 s53, s53, 0
	ds_read_b128 v[222:225], v12 offset:496
	ds_read_b128 v[226:229], v12 offset:8688
	ds_read_b128 v[230:233], v12 offset:16880
	s_waitcnt vmcnt(59) lgkmcnt(9)
	v_fmac_f32_e32 v6, v176, v186
	v_fmac_f32_e32 v7, v176, v190
	v_fmac_f32_e32 v11, v176, v194
	global_load_dword v176, v184, s[52:53]
	s_add_u32 s52, s52, 0x6000
	s_addc_u32 s53, s53, 0
	s_waitcnt vmcnt(59)
	v_fmac_f32_e32 v6, v177, v187
	v_fmac_f32_e32 v7, v177, v191
	v_fmac_f32_e32 v11, v177, v195
	global_load_dword v177, v184, s[52:53]
	s_add_u32 s52, s52, 0x6000
	s_addc_u32 s53, s53, 0
	s_waitcnt vmcnt(59)
	v_fmac_f32_e32 v6, v178, v188
	v_fmac_f32_e32 v7, v178, v192
	v_fmac_f32_e32 v11, v178, v196
	global_load_dword v178, v184, s[52:53]
	s_add_u32 s52, s52, 0x6000
	s_addc_u32 s53, s53, 0
	s_waitcnt vmcnt(59)
	v_fmac_f32_e32 v6, v179, v189
	v_fmac_f32_e32 v7, v179, v193
	v_fmac_f32_e32 v11, v179, v197
	global_load_dword v179, v184, s[52:53]
	s_add_u32 s52, s52, 0x6000
	s_addc_u32 s53, s53, 0
	ds_read_b128 v[186:189], v12 offset:512
	ds_read_b128 v[190:193], v12 offset:8704
	ds_read_b128 v[194:197], v12 offset:16896
	s_waitcnt vmcnt(59) lgkmcnt(9)
	v_fmac_f32_e32 v6, v180, v198
	v_fmac_f32_e32 v7, v180, v202
	v_fmac_f32_e32 v11, v180, v206
	global_load_dword v180, v184, s[52:53]
	s_add_u32 s52, s52, 0x6000
	s_addc_u32 s53, s53, 0
	s_waitcnt vmcnt(59)
	v_fmac_f32_e32 v6, v181, v199
	v_fmac_f32_e32 v7, v181, v203
	v_fmac_f32_e32 v11, v181, v207
	global_load_dword v181, v184, s[52:53]
	s_add_u32 s52, s52, 0x6000
	s_addc_u32 s53, s53, 0
	s_waitcnt vmcnt(59)
	v_fmac_f32_e32 v6, v182, v200
	v_fmac_f32_e32 v7, v182, v204
	v_fmac_f32_e32 v11, v182, v208
	global_load_dword v182, v184, s[52:53]
	s_add_u32 s52, s52, 0x6000
	s_addc_u32 s53, s53, 0
	s_waitcnt vmcnt(59)
	v_fmac_f32_e32 v6, v183, v201
	v_fmac_f32_e32 v7, v183, v205
	v_fmac_f32_e32 v11, v183, v209
	global_load_dword v183, v184, s[52:53]
	s_add_u32 s52, s52, 0x6000
	s_addc_u32 s53, s53, 0
	ds_read_b128 v[198:201], v12 offset:528
	ds_read_b128 v[202:205], v12 offset:8720
	ds_read_b128 v[206:209], v12 offset:16912
	s_waitcnt vmcnt(59) lgkmcnt(9)
; __device__ __forceinline__ void mod_item(PREF P, int l, int nt, float* sm) {
;     ...
;     float a0 = 0.f, a1 = 0.f, a2 = 0.f;
; #pragma unroll 16
;     for (int k = kg * 256; k < kg * 256 + 256; ++k) { const float wv = w[(size_t)k * 6144]; a0 += sc[k] * wv; a1 += sc[2048 + k] * wv; a2 += sc[4096 + k] * wv; }
	v_fmac_f32_e32 v6, v124, v210
	v_fmac_f32_e32 v7, v124, v214
	v_fmac_f32_e32 v11, v124, v218
	global_load_dword v124, v184, s[52:53]
	s_add_u32 s52, s52, 0x6000
	s_addc_u32 s53, s53, 0
	s_waitcnt vmcnt(59)
	v_fmac_f32_e32 v6, v125, v211
	v_fmac_f32_e32 v7, v125, v215
	v_fmac_f32_e32 v11, v125, v219
	global_load_dword v125, v184, s[52:53]
	s_add_u32 s52, s52, 0x6000
	s_addc_u32 s53, s53, 0
	s_waitcnt vmcnt(59)
	v_fmac_f32_e32 v6, v126, v212
	v_fmac_f32_e32 v7, v126, v216
	v_fmac_f32_e32 v11, v126, v220
	global_load_dword v126, v184, s[52:53]
	s_add_u32 s52, s52, 0x6000
	s_addc_u32 s53, s53, 0
	s_waitcnt vmcnt(59)
	v_fmac_f32_e32 v6, v127, v213
	v_fmac_f32_e32 v7, v127, v217
	v_fmac_f32_e32 v11, v127, v221
	global_load_dword v127, v184, s[52:53]
	s_add_u32 s52, s52, 0x6000
	s_addc_u32 s53, s53, 0
	ds_read_b128 v[210:213], v12 offset:544
	ds_read_b128 v[214:217], v12 offset:8736
	ds_read_b128 v[218:221], v12 offset:16928
	s_waitcnt vmcnt(59) lgkmcnt(9)
	v_fmac_f32_e32 v6, v128, v222
	v_fmac_f32_e32 v7, v128, v226
	v_fmac_f32_e32 v11, v128, v230
	global_load_dword v128, v184, s[52:53]
	s_add_u32 s52, s52, 0x6000
	s_addc_u32 s53, s53, 0
	s_waitcnt vmcnt(59)
	v_fmac_f32_e32 v6, v129, v223
	v_fmac_f32_e32 v7, v129, v227
	v_fmac_f32_e32 v11, v129, v231
	global_load_dword v129, v184, s[52:53]
	s_add_u32 s52, s52, 0x6000
	s_addc_u32 s53, s53, 0
	s_waitcnt vmcnt(59)
	v_fmac_f32_e32 v6, v130, v224
	v_fmac_f32_e32 v7, v130, v228
	v_fmac_f32_e32 v11, v130, v232
	global_load_dword v130, v184, s[52:53]
	s_add_u32 s52, s52, 0x6000
	s_addc_u32 s53, s53, 0
	s_waitcnt vmcnt(59)
	v_fmac_f32_e32 v6, v131, v225
	v_fmac_f32_e32 v7, v131, v229
	v_fmac_f32_e32 v11, v131, v233
	global_load_dword v131, v184, s[52:53]
	s_add_u32 s52, s52, 0x6000
	s_addc_u32 s53, s53, 0
	ds_read_b128 v[222:225], v12 offset:560
	ds_read_b128 v[226:229], v12 offset:8752
	ds_read_b128 v[230:233], v12 offset:16944
	s_waitcnt vmcnt(59) lgkmcnt(9)
	v_fmac_f32_e32 v6, v132, v186
	v_fmac_f32_e32 v7, v132, v190
	v_fmac_f32_e32 v11, v132, v194
	global_load_dword v132, v184, s[52:53]
	s_add_u32 s52, s52, 0x6000
	s_addc_u32 s53, s53, 0
	s_waitcnt vmcnt(59)
	v_fmac_f32_e32 v6, v133, v187
	v_fmac_f32_e32 v7, v133, v191
	v_fmac_f32_e32 v11, v133, v195
	global_load_dword v133, v184, s[52:53]
	s_add_u32 s52, s52, 0x6000
	s_addc_u32 s53, s53, 0
	s_waitcnt vmcnt(59)
	v_fmac_f32_e32 v6, v134, v188
	v_fmac_f32_e32 v7, v134, v192
	v_fmac_f32_e32 v11, v134, v196
	global_load_dword v134, v184, s[52:53]
	s_add_u32 s52, s52, 0x6000
	s_addc_u32 s53, s53, 0
	s_waitcnt vmcnt(59)
	v_fmac_f32_e32 v6, v135, v189
	v_fmac_f32_e32 v7, v135, v193
	v_fmac_f32_e32 v11, v135, v197
	global_load_dword v135, v184, s[52:53]
	s_add_u32 s52, s52, 0x6000
	s_addc_u32 s53, s53, 0
	ds_read_b128 v[186:189], v12 offset:576
	ds_read_b128 v[190:193], v12 offset:8768
	ds_read_b128 v[194:197], v12 offset:16960
	s_waitcnt vmcnt(59) lgkmcnt(9)
	v_fmac_f32_e32 v6, v136, v198
	v_fmac_f32_e32 v7, v136, v202
	v_fmac_f32_e32 v11, v136, v206
	global_load_dword v136, v184, s[52:53]
	s_add_u32 s52, s52, 0x6000
	s_addc_u32 s53, s53, 0
	s_waitcnt vmcnt(59)
	v_fmac_f32_e32 v6, v137, v199
	v_fmac_f32_e32 v7, v137, v203
	v_fmac_f32_e32 v11, v137, v207
	global_load_dword v137, v184, s[52:53]
	s_add_u32 s52, s52, 0x6000
	s_addc_u32 s53, s53, 0
	s_waitcnt vmcnt(59)
	v_fmac_f32_e32 v6, v138, v200
	v_fmac_f32_e32 v7, v138, v204
	v_fmac_f32_e32 v11, v138, v208
	global_load_dword v138, v184, s[52:53]
	s_add_u32 s52, s52, 0x6000
	s_addc_u32 s53, s53, 0
	s_waitcnt vmcnt(59)
	v_fmac_f32_e32 v6, v139, v201
	v_fmac_f32_e32 v7, v139, v205
	v_fmac_f32_e32 v11, v139, v209
	global_load_dword v139, v184, s[52:53]
	s_add_u32 s52, s52, 0x6000
	s_addc_u32 s53, s53, 0
	ds_read_b128 v[198:201], v12 offset:592
	ds_read_b128 v[202:205], v12 offset:8784
	ds_read_b128 v[206:209], v12 offset:16976
	s_waitcnt vmcnt(59) lgkmcnt(9)
	v_fmac_f32_e32 v6, v140, v210
	v_fmac_f32_e32 v7, v140, v214
	v_fmac_f32_e32 v11, v140, v218
	global_load_dword v140, v184, s[52:53]
	s_add_u32 s52, s52, 0x6000
	s_addc_u32 s53, s53, 0
	s_waitcnt vmcnt(59)
	v_fmac_f32_e32 v6, v141, v211
	v_fmac_f32_e32 v7, v141, v215
	v_fmac_f32_e32 v11, v141, v219
	global_load_dword v141, v184, s[52:53]
	s_add_u32 s52, s52, 0x6000
	s_addc_u32 s53, s53, 0
	s_waitcnt vmcnt(59)
	v_fmac_f32_e32 v6, v142, v212
	v_fmac_f32_e32 v7, v142, v216
	v_fmac_f32_e32 v11, v142, v220
	global_load_dword v142, v184, s[52:53]
	s_add_u32 s52, s52, 0x6000
	s_addc_u32 s53, s53, 0
	s_waitcnt vmcnt(59)
	v_fmac_f32_e32 v6, v143, v213
	v_fmac_f32_e32 v7, v143, v217
	v_fmac_f32_e32 v11, v143, v221
	global_load_dword v143, v184, s[52:53]
	s_add_u32 s52, s52, 0x6000
	s_addc_u32 s53, s53, 0
	ds_read_b128 v[210:213], v12 offset:608
	ds_read_b128 v[214:217], v12 offset:8800
	ds_read_b128 v[218:221], v12 offset:16992
	s_waitcnt vmcnt(59) lgkmcnt(9)
	v_fmac_f32_e32 v6, v144, v222
	v_fmac_f32_e32 v7, v144, v226
	v_fmac_f32_e32 v11, v144, v230
	global_load_dword v144, v184, s[52:53]
	s_add_u32 s52, s52, 0x6000
	s_addc_u32 s53, s53, 0
	s_waitcnt vmcnt(59)
	v_fmac_f32_e32 v6, v145, v223
	v_fmac_f32_e32 v7, v145, v227
	v_fmac_f32_e32 v11, v145, v231
	global_load_dword v145, v184, s[52:53]
	s_add_u32 s52, s52, 0x6000
	s_addc_u32 s53, s53, 0
	s_waitcnt vmcnt(59)
	v_fmac_f32_e32 v6, v146, v224
	v_fmac_f32_e32 v7, v146, v228
	v_fmac_f32_e32 v11, v146, v232
	global_load_dword v146, v184, s[52:53]
	s_add_u32 s52, s52, 0x6000
	s_addc_u32 s53, s53, 0
	s_waitcnt vmcnt(59)
	v_fmac_f32_e32 v6, v147, v225
	v_fmac_f32_e32 v7, v147, v229
	v_fmac_f32_e32 v11, v147, v233
	global_load_dword v147, v184, s[52:53]
	s_add_u32 s52, s52, 0x6000
	s_addc_u32 s53, s53, 0
	ds_read_b128 v[222:225], v12 offset:624
	ds_read_b128 v[226:229], v12 offset:8816
	ds_read_b128 v[230:233], v12 offset:17008
	s_waitcnt vmcnt(59) lgkmcnt(9)
; __device__ __forceinline__ void mod_item(PREF P, int l, int nt, float* sm) {
;     ...
;     float a0 = 0.f, a1 = 0.f, a2 = 0.f;
; #pragma unroll 16
;     for (int k = kg * 256; k < kg * 256 + 256; ++k) { const float wv = w[(size_t)k * 6144]; a0 += sc[k] * wv; a1 += sc[2048 + k] * wv; a2 += sc[4096 + k] * wv; }
	v_fmac_f32_e32 v6, v148, v186
	v_fmac_f32_e32 v7, v148, v190
	v_fmac_f32_e32 v11, v148, v194
	global_load_dword v148, v184, s[52:53]
	s_add_u32 s52, s52, 0x6000
	s_addc_u32 s53, s53, 0
	s_waitcnt vmcnt(59)
	v_fmac_f32_e32 v6, v149, v187
	v_fmac_f32_e32 v7, v149, v191
	v_fmac_f32_e32 v11, v149, v195
	global_load_dword v149, v184, s[52:53]
	s_add_u32 s52, s52, 0x6000
	s_addc_u32 s53, s53, 0
	s_waitcnt vmcnt(59)
	v_fmac_f32_e32 v6, v150, v188
	v_fmac_f32_e32 v7, v150, v192
	v_fmac_f32_e32 v11, v150, v196
	global_load_dword v150, v184, s[52:53]
	s_add_u32 s52, s52, 0x6000
	s_addc_u32 s53, s53, 0
	s_waitcnt vmcnt(59)
	v_fmac_f32_e32 v6, v151, v189
	v_fmac_f32_e32 v7, v151, v193
	v_fmac_f32_e32 v11, v151, v197
	global_load_dword v151, v184, s[52:53]
	s_add_u32 s52, s52, 0x6000
	s_addc_u32 s53, s53, 0
	ds_read_b128 v[186:189], v12 offset:640
	ds_read_b128 v[190:193], v12 offset:8832
	ds_read_b128 v[194:197], v12 offset:17024
	s_waitcnt vmcnt(59) lgkmcnt(9)
	v_fmac_f32_e32 v6, v152, v198
	v_fmac_f32_e32 v7, v152, v202
	v_fmac_f32_e32 v11, v152, v206
	global_load_dword v152, v184, s[52:53]
	s_add_u32 s52, s52, 0x6000
	s_addc_u32 s53, s53, 0
	s_waitcnt vmcnt(59)
	v_fmac_f32_e32 v6, v153, v199
	v_fmac_f32_e32 v7, v153, v203
	v_fmac_f32_e32 v11, v153, v207
	global_load_dword v153, v184, s[52:53]
	s_add_u32 s52, s52, 0x6000
	s_addc_u32 s53, s53, 0
	s_waitcnt vmcnt(59)
	v_fmac_f32_e32 v6, v154, v200
	v_fmac_f32_e32 v7, v154, v204
	v_fmac_f32_e32 v11, v154, v208
	global_load_dword v154, v184, s[52:53]
	s_add_u32 s52, s52, 0x6000
	s_addc_u32 s53, s53, 0
	s_waitcnt vmcnt(59)
	v_fmac_f32_e32 v6, v155, v201
	v_fmac_f32_e32 v7, v155, v205
	v_fmac_f32_e32 v11, v155, v209
	global_load_dword v155, v184, s[52:53]
	s_add_u32 s52, s52, 0x6000
	s_addc_u32 s53, s53, 0
	ds_read_b128 v[198:201], v12 offset:656
	ds_read_b128 v[202:205], v12 offset:8848
	ds_read_b128 v[206:209], v12 offset:17040
	s_waitcnt vmcnt(59) lgkmcnt(9)
	v_fmac_f32_e32 v6, v156, v210
	v_fmac_f32_e32 v7, v156, v214
	v_fmac_f32_e32 v11, v156, v218
	global_load_dword v156, v184, s[52:53]
	s_add_u32 s52, s52, 0x6000
	s_addc_u32 s53, s53, 0
	s_waitcnt vmcnt(59)
	v_fmac_f32_e32 v6, v157, v211
	v_fmac_f32_e32 v7, v157, v215
	v_fmac_f32_e32 v11, v157, v219
	global_load_dword v157, v184, s[52:53]
	s_add_u32 s52, s52, 0x6000
	s_addc_u32 s53, s53, 0
	s_waitcnt vmcnt(59)
	v_fmac_f32_e32 v6, v158, v212
	v_fmac_f32_e32 v7, v158, v216
	v_fmac_f32_e32 v11, v158, v220
	global_load_dword v158, v184, s[52:53]
	s_add_u32 s52, s52, 0x6000
	s_addc_u32 s53, s53, 0
	s_waitcnt vmcnt(59)
	v_fmac_f32_e32 v6, v159, v213
	v_fmac_f32_e32 v7, v159, v217
	v_fmac_f32_e32 v11, v159, v221
	global_load_dword v159, v184, s[52:53]
	s_add_u32 s52, s52, 0x6000
	s_addc_u32 s53, s53, 0
	ds_read_b128 v[210:213], v12 offset:672
	ds_read_b128 v[214:217], v12 offset:8864
	ds_read_b128 v[218:221], v12 offset:17056
	s_waitcnt vmcnt(59) lgkmcnt(9)
	v_fmac_f32_e32 v6, v160, v222
	v_fmac_f32_e32 v7, v160, v226
	v_fmac_f32_e32 v11, v160, v230
	global_load_dword v160, v184, s[52:53]
	s_add_u32 s52, s52, 0x6000
	s_addc_u32 s53, s53, 0
	s_waitcnt vmcnt(59)
	v_fmac_f32_e32 v6, v161, v223
	v_fmac_f32_e32 v7, v161, v227
	v_fmac_f32_e32 v11, v161, v231
	global_load_dword v161, v184, s[52:53]
	s_add_u32 s52, s52, 0x6000
	s_addc_u32 s53, s53, 0
	s_waitcnt vmcnt(59)
	v_fmac_f32_e32 v6, v162, v224
	v_fmac_f32_e32 v7, v162, v228
	v_fmac_f32_e32 v11, v162, v232
	global_load_dword v162, v184, s[52:53]
	s_add_u32 s52, s52, 0x6000
	s_addc_u32 s53, s53, 0
	s_waitcnt vmcnt(59)
	v_fmac_f32_e32 v6, v163, v225
	v_fmac_f32_e32 v7, v163, v229
	v_fmac_f32_e32 v11, v163, v233
	global_load_dword v163, v184, s[52:53]
	s_add_u32 s52, s52, 0x6000
	s_addc_u32 s53, s53, 0
	ds_read_b128 v[222:225], v12 offset:688
	ds_read_b128 v[226:229], v12 offset:8880
	ds_read_b128 v[230:233], v12 offset:17072
	s_waitcnt vmcnt(59) lgkmcnt(9)
	v_fmac_f32_e32 v6, v164, v186
	v_fmac_f32_e32 v7, v164, v190
	v_fmac_f32_e32 v11, v164, v194
	global_load_dword v164, v184, s[52:53]
	s_add_u32 s52, s52, 0x6000
	s_addc_u32 s53, s53, 0
	s_waitcnt vmcnt(59)
	v_fmac_f32_e32 v6, v165, v187
	v_fmac_f32_e32 v7, v165, v191
	v_fmac_f32_e32 v11, v165, v195
	global_load_dword v165, v184, s[52:53]
	s_add_u32 s52, s52, 0x6000
	s_addc_u32 s53, s53, 0
	s_waitcnt vmcnt(59)
	v_fmac_f32_e32 v6, v166, v188
	v_fmac_f32_e32 v7, v166, v192
	v_fmac_f32_e32 v11, v166, v196
	global_load_dword v166, v184, s[52:53]
	s_add_u32 s52, s52, 0x6000
	s_addc_u32 s53, s53, 0
	s_waitcnt vmcnt(59)
	v_fmac_f32_e32 v6, v167, v189
	v_fmac_f32_e32 v7, v167, v193
	v_fmac_f32_e32 v11, v167, v197
	global_load_dword v167, v184, s[52:53]
	s_add_u32 s52, s52, 0x6000
	s_addc_u32 s53, s53, 0
	ds_read_b128 v[186:189], v12 offset:704
	ds_read_b128 v[190:193], v12 offset:8896
	ds_read_b128 v[194:197], v12 offset:17088
	s_waitcnt vmcnt(59) lgkmcnt(9)
	v_fmac_f32_e32 v6, v168, v198
	v_fmac_f32_e32 v7, v168, v202
	v_fmac_f32_e32 v11, v168, v206
	global_load_dword v168, v184, s[52:53]
	s_add_u32 s52, s52, 0x6000
	s_addc_u32 s53, s53, 0
	s_waitcnt vmcnt(59)
	v_fmac_f32_e32 v6, v169, v199
	v_fmac_f32_e32 v7, v169, v203
	v_fmac_f32_e32 v11, v169, v207
	global_load_dword v169, v184, s[52:53]
	s_add_u32 s52, s52, 0x6000
	s_addc_u32 s53, s53, 0
	s_waitcnt vmcnt(59)
	v_fmac_f32_e32 v6, v170, v200
	v_fmac_f32_e32 v7, v170, v204
	v_fmac_f32_e32 v11, v170, v208
	global_load_dword v170, v184, s[52:53]
	s_add_u32 s52, s52, 0x6000
	s_addc_u32 s53, s53, 0
	s_waitcnt vmcnt(59)
	v_fmac_f32_e32 v6, v171, v201
	v_fmac_f32_e32 v7, v171, v205
	v_fmac_f32_e32 v11, v171, v209
	global_load_dword v171, v184, s[52:53]
	s_add_u32 s52, s52, 0x6000
	s_addc_u32 s53, s53, 0
	ds_read_b128 v[198:201], v12 offset:720
	ds_read_b128 v[202:205], v12 offset:8912
	ds_read_b128 v[206:209], v12 offset:17104
	s_waitcnt vmcnt(59) lgkmcnt(9)
; __device__ __forceinline__ void mod_item(PREF P, int l, int nt, float* sm) {
;     ...
;     float a0 = 0.f, a1 = 0.f, a2 = 0.f;
; #pragma unroll 16
;     for (int k = kg * 256; k < kg * 256 + 256; ++k) { const float wv = w[(size_t)k * 6144]; a0 += sc[k] * wv; a1 += sc[2048 + k] * wv; a2 += sc[4096 + k] * wv; }
	v_fmac_f32_e32 v6, v172, v210
	v_fmac_f32_e32 v7, v172, v214
	v_fmac_f32_e32 v11, v172, v218
	global_load_dword v172, v184, s[52:53]
	s_add_u32 s52, s52, 0x6000
	s_addc_u32 s53, s53, 0
	s_waitcnt vmcnt(59)
	v_fmac_f32_e32 v6, v173, v211
	v_fmac_f32_e32 v7, v173, v215
	v_fmac_f32_e32 v11, v173, v219
	global_load_dword v173, v184, s[52:53]
	s_add_u32 s52, s52, 0x6000
	s_addc_u32 s53, s53, 0
	s_waitcnt vmcnt(59)
	v_fmac_f32_e32 v6, v174, v212
	v_fmac_f32_e32 v7, v174, v216
	v_fmac_f32_e32 v11, v174, v220
	global_load_dword v174, v184, s[52:53]
	s_add_u32 s52, s52, 0x6000
	s_addc_u32 s53, s53, 0
	s_waitcnt vmcnt(59)
	v_fmac_f32_e32 v6, v175, v213
	v_fmac_f32_e32 v7, v175, v217
	v_fmac_f32_e32 v11, v175, v221
	global_load_dword v175, v184, s[52:53]
	s_add_u32 s52, s52, 0x6000
	s_addc_u32 s53, s53, 0
	ds_read_b128 v[210:213], v12 offset:736
	ds_read_b128 v[214:217], v12 offset:8928
	ds_read_b128 v[218:221], v12 offset:17120
	s_waitcnt vmcnt(59) lgkmcnt(9)
	v_fmac_f32_e32 v6, v176, v222
	v_fmac_f32_e32 v7, v176, v226
	v_fmac_f32_e32 v11, v176, v230
	global_load_dword v176, v184, s[52:53]
	s_add_u32 s52, s52, 0x6000
	s_addc_u32 s53, s53, 0
	s_waitcnt vmcnt(59)
	v_fmac_f32_e32 v6, v177, v223
	v_fmac_f32_e32 v7, v177, v227
	v_fmac_f32_e32 v11, v177, v231
	global_load_dword v177, v184, s[52:53]
	s_add_u32 s52, s52, 0x6000
	s_addc_u32 s53, s53, 0
	s_waitcnt vmcnt(59)
	v_fmac_f32_e32 v6, v178, v224
	v_fmac_f32_e32 v7, v178, v228
	v_fmac_f32_e32 v11, v178, v232
	global_load_dword v178, v184, s[52:53]
	s_add_u32 s52, s52, 0x6000
	s_addc_u32 s53, s53, 0
	s_waitcnt vmcnt(59)
	v_fmac_f32_e32 v6, v179, v225
	v_fmac_f32_e32 v7, v179, v229
	v_fmac_f32_e32 v11, v179, v233
	global_load_dword v179, v184, s[52:53]
	s_add_u32 s52, s52, 0x6000
	s_addc_u32 s53, s53, 0
	ds_read_b128 v[222:225], v12 offset:752
	ds_read_b128 v[226:229], v12 offset:8944
	ds_read_b128 v[230:233], v12 offset:17136
	s_waitcnt vmcnt(59) lgkmcnt(9)
	v_fmac_f32_e32 v6, v180, v186
	v_fmac_f32_e32 v7, v180, v190
	v_fmac_f32_e32 v11, v180, v194
	global_load_dword v180, v184, s[52:53]
	s_add_u32 s52, s52, 0x6000
	s_addc_u32 s53, s53, 0
	s_waitcnt vmcnt(59)
	v_fmac_f32_e32 v6, v181, v187
	v_fmac_f32_e32 v7, v181, v191
	v_fmac_f32_e32 v11, v181, v195
	global_load_dword v181, v184, s[52:53]
	s_add_u32 s52, s52, 0x6000
	s_addc_u32 s53, s53, 0
	s_waitcnt vmcnt(59)
	v_fmac_f32_e32 v6, v182, v188
	v_fmac_f32_e32 v7, v182, v192
	v_fmac_f32_e32 v11, v182, v196
	global_load_dword v182, v184, s[52:53]
	s_add_u32 s52, s52, 0x6000
	s_addc_u32 s53, s53, 0
	s_waitcnt vmcnt(59)
	v_fmac_f32_e32 v6, v183, v189
	v_fmac_f32_e32 v7, v183, v193
	v_fmac_f32_e32 v11, v183, v197
	global_load_dword v183, v184, s[52:53]
	s_add_u32 s52, s52, 0x6000
	s_addc_u32 s53, s53, 0
	ds_read_b128 v[186:189], v12 offset:768
	ds_read_b128 v[190:193], v12 offset:8960
	ds_read_b128 v[194:197], v12 offset:17152
	s_waitcnt vmcnt(59) lgkmcnt(9)
	v_fmac_f32_e32 v6, v124, v198
	v_fmac_f32_e32 v7, v124, v202
	v_fmac_f32_e32 v11, v124, v206
	global_load_dword v124, v184, s[52:53]
	s_add_u32 s52, s52, 0x6000
	s_addc_u32 s53, s53, 0
	s_waitcnt vmcnt(59)
	v_fmac_f32_e32 v6, v125, v199
	v_fmac_f32_e32 v7, v125, v203
	v_fmac_f32_e32 v11, v125, v207
	global_load_dword v125, v184, s[52:53]
	s_add_u32 s52, s52, 0x6000
	s_addc_u32 s53, s53, 0
	s_waitcnt vmcnt(59)
	v_fmac_f32_e32 v6, v126, v200
	v_fmac_f32_e32 v7, v126, v204
	v_fmac_f32_e32 v11, v126, v208
	global_load_dword v126, v184, s[52:53]
	s_add_u32 s52, s52, 0x6000
	s_addc_u32 s53, s53, 0
	s_waitcnt vmcnt(59)
	v_fmac_f32_e32 v6, v127, v201
	v_fmac_f32_e32 v7, v127, v205
	v_fmac_f32_e32 v11, v127, v209
	global_load_dword v127, v184, s[52:53]
	s_add_u32 s52, s52, 0x6000
	s_addc_u32 s53, s53, 0
	ds_read_b128 v[198:201], v12 offset:784
	ds_read_b128 v[202:205], v12 offset:8976
	ds_read_b128 v[206:209], v12 offset:17168
	s_waitcnt vmcnt(59) lgkmcnt(9)
	v_fmac_f32_e32 v6, v128, v210
	v_fmac_f32_e32 v7, v128, v214
	v_fmac_f32_e32 v11, v128, v218
	global_load_dword v128, v184, s[52:53]
	s_add_u32 s52, s52, 0x6000
	s_addc_u32 s53, s53, 0
	s_waitcnt vmcnt(59)
	v_fmac_f32_e32 v6, v129, v211
	v_fmac_f32_e32 v7, v129, v215
	v_fmac_f32_e32 v11, v129, v219
	global_load_dword v129, v184, s[52:53]
	s_add_u32 s52, s52, 0x6000
	s_addc_u32 s53, s53, 0
	s_waitcnt vmcnt(59)
	v_fmac_f32_e32 v6, v130, v212
	v_fmac_f32_e32 v7, v130, v216
	v_fmac_f32_e32 v11, v130, v220
	global_load_dword v130, v184, s[52:53]
	s_add_u32 s52, s52, 0x6000
	s_addc_u32 s53, s53, 0
	s_waitcnt vmcnt(59)
	v_fmac_f32_e32 v6, v131, v213
	v_fmac_f32_e32 v7, v131, v217
	v_fmac_f32_e32 v11, v131, v221
	global_load_dword v131, v184, s[52:53]
	s_add_u32 s52, s52, 0x6000
	s_addc_u32 s53, s53, 0
	ds_read_b128 v[210:213], v12 offset:800
	ds_read_b128 v[214:217], v12 offset:8992
	ds_read_b128 v[218:221], v12 offset:17184
	s_waitcnt vmcnt(59) lgkmcnt(9)
	v_fmac_f32_e32 v6, v132, v222
	v_fmac_f32_e32 v7, v132, v226
	v_fmac_f32_e32 v11, v132, v230
	global_load_dword v132, v184, s[52:53]
	s_add_u32 s52, s52, 0x6000
	s_addc_u32 s53, s53, 0
	s_waitcnt vmcnt(59)
	v_fmac_f32_e32 v6, v133, v223
	v_fmac_f32_e32 v7, v133, v227
	v_fmac_f32_e32 v11, v133, v231
	global_load_dword v133, v184, s[52:53]
	s_add_u32 s52, s52, 0x6000
	s_addc_u32 s53, s53, 0
	s_waitcnt vmcnt(59)
	v_fmac_f32_e32 v6, v134, v224
	v_fmac_f32_e32 v7, v134, v228
	v_fmac_f32_e32 v11, v134, v232
	global_load_dword v134, v184, s[52:53]
	s_add_u32 s52, s52, 0x6000
	s_addc_u32 s53, s53, 0
	s_waitcnt vmcnt(59)
	v_fmac_f32_e32 v6, v135, v225
	v_fmac_f32_e32 v7, v135, v229
	v_fmac_f32_e32 v11, v135, v233
	global_load_dword v135, v184, s[52:53]
	s_add_u32 s52, s52, 0x6000
	s_addc_u32 s53, s53, 0
	ds_read_b128 v[222:225], v12 offset:816
	ds_read_b128 v[226:229], v12 offset:9008
	ds_read_b128 v[230:233], v12 offset:17200
	s_waitcnt vmcnt(59) lgkmcnt(9)
; __device__ __forceinline__ void mod_item(PREF P, int l, int nt, float* sm) {
;     ...
;     float a0 = 0.f, a1 = 0.f, a2 = 0.f;
; #pragma unroll 16
;     for (int k = kg * 256; k < kg * 256 + 256; ++k) { const float wv = w[(size_t)k * 6144]; a0 += sc[k] * wv; a1 += sc[2048 + k] * wv; a2 += sc[4096 + k] * wv; }
	v_fmac_f32_e32 v6, v136, v186
	v_fmac_f32_e32 v7, v136, v190
	v_fmac_f32_e32 v11, v136, v194
	global_load_dword v136, v184, s[52:53]
	s_add_u32 s52, s52, 0x6000
	s_addc_u32 s53, s53, 0
	s_waitcnt vmcnt(59)
	v_fmac_f32_e32 v6, v137, v187
	v_fmac_f32_e32 v7, v137, v191
	v_fmac_f32_e32 v11, v137, v195
	global_load_dword v137, v184, s[52:53]
	s_add_u32 s52, s52, 0x6000
	s_addc_u32 s53, s53, 0
	s_waitcnt vmcnt(59)
	v_fmac_f32_e32 v6, v138, v188
	v_fmac_f32_e32 v7, v138, v192
	v_fmac_f32_e32 v11, v138, v196
	global_load_dword v138, v184, s[52:53]
	s_add_u32 s52, s52, 0x6000
	s_addc_u32 s53, s53, 0
	s_waitcnt vmcnt(59)
	v_fmac_f32_e32 v6, v139, v189
	v_fmac_f32_e32 v7, v139, v193
	v_fmac_f32_e32 v11, v139, v197
	global_load_dword v139, v184, s[52:53]
	s_add_u32 s52, s52, 0x6000
	s_addc_u32 s53, s53, 0
	ds_read_b128 v[186:189], v12 offset:832
	ds_read_b128 v[190:193], v12 offset:9024
	ds_read_b128 v[194:197], v12 offset:17216
	s_waitcnt vmcnt(59) lgkmcnt(9)
	v_fmac_f32_e32 v6, v140, v198
	v_fmac_f32_e32 v7, v140, v202
	v_fmac_f32_e32 v11, v140, v206
	s_waitcnt vmcnt(58)
	v_fmac_f32_e32 v6, v141, v199
	v_fmac_f32_e32 v7, v141, v203
	v_fmac_f32_e32 v11, v141, v207
	s_waitcnt vmcnt(57)
	v_fmac_f32_e32 v6, v142, v200
	v_fmac_f32_e32 v7, v142, v204
	v_fmac_f32_e32 v11, v142, v208
	s_waitcnt vmcnt(56)
	v_fmac_f32_e32 v6, v143, v201
	v_fmac_f32_e32 v7, v143, v205
	v_fmac_f32_e32 v11, v143, v209
	ds_read_b128 v[198:201], v12 offset:848
	ds_read_b128 v[202:205], v12 offset:9040
	ds_read_b128 v[206:209], v12 offset:17232
	s_waitcnt vmcnt(55) lgkmcnt(9)
	v_fmac_f32_e32 v6, v144, v210
	v_fmac_f32_e32 v7, v144, v214
	v_fmac_f32_e32 v11, v144, v218
	s_waitcnt vmcnt(54)
	v_fmac_f32_e32 v6, v145, v211
	v_fmac_f32_e32 v7, v145, v215
	v_fmac_f32_e32 v11, v145, v219
	s_waitcnt vmcnt(53)
	v_fmac_f32_e32 v6, v146, v212
	v_fmac_f32_e32 v7, v146, v216
	v_fmac_f32_e32 v11, v146, v220
	s_waitcnt vmcnt(52)
	v_fmac_f32_e32 v6, v147, v213
	v_fmac_f32_e32 v7, v147, v217
	v_fmac_f32_e32 v11, v147, v221
	ds_read_b128 v[210:213], v12 offset:864
	ds_read_b128 v[214:217], v12 offset:9056
	ds_read_b128 v[218:221], v12 offset:17248
	s_waitcnt vmcnt(51) lgkmcnt(9)
	v_fmac_f32_e32 v6, v148, v222
	v_fmac_f32_e32 v7, v148, v226
	v_fmac_f32_e32 v11, v148, v230
	s_waitcnt vmcnt(50)
	v_fmac_f32_e32 v6, v149, v223
	v_fmac_f32_e32 v7, v149, v227
	v_fmac_f32_e32 v11, v149, v231
	s_waitcnt vmcnt(49)
	v_fmac_f32_e32 v6, v150, v224
	v_fmac_f32_e32 v7, v150, v228
	v_fmac_f32_e32 v11, v150, v232
	s_waitcnt vmcnt(48)
	v_fmac_f32_e32 v6, v151, v225
	v_fmac_f32_e32 v7, v151, v229
	v_fmac_f32_e32 v11, v151, v233
	ds_read_b128 v[222:225], v12 offset:880
	ds_read_b128 v[226:229], v12 offset:9072
	ds_read_b128 v[230:233], v12 offset:17264
	s_waitcnt vmcnt(47) lgkmcnt(9)
	v_fmac_f32_e32 v6, v152, v186
	v_fmac_f32_e32 v7, v152, v190
	v_fmac_f32_e32 v11, v152, v194
	s_waitcnt vmcnt(46)
	v_fmac_f32_e32 v6, v153, v187
	v_fmac_f32_e32 v7, v153, v191
	v_fmac_f32_e32 v11, v153, v195
	s_waitcnt vmcnt(45)
	v_fmac_f32_e32 v6, v154, v188
	v_fmac_f32_e32 v7, v154, v192
	v_fmac_f32_e32 v11, v154, v196
	s_waitcnt vmcnt(44)
	v_fmac_f32_e32 v6, v155, v189
	v_fmac_f32_e32 v7, v155, v193
	v_fmac_f32_e32 v11, v155, v197
	ds_read_b128 v[186:189], v12 offset:896
	ds_read_b128 v[190:193], v12 offset:9088
	ds_read_b128 v[194:197], v12 offset:17280
	s_waitcnt vmcnt(43) lgkmcnt(9)
	v_fmac_f32_e32 v6, v156, v198
	v_fmac_f32_e32 v7, v156, v202
	v_fmac_f32_e32 v11, v156, v206
	s_waitcnt vmcnt(42)
	v_fmac_f32_e32 v6, v157, v199
	v_fmac_f32_e32 v7, v157, v203
	v_fmac_f32_e32 v11, v157, v207
	s_waitcnt vmcnt(41)
	v_fmac_f32_e32 v6, v158, v200
	v_fmac_f32_e32 v7, v158, v204
	v_fmac_f32_e32 v11, v158, v208
	s_waitcnt vmcnt(40)
	v_fmac_f32_e32 v6, v159, v201
	v_fmac_f32_e32 v7, v159, v205
	v_fmac_f32_e32 v11, v159, v209
	ds_read_b128 v[198:201], v12 offset:912
	ds_read_b128 v[202:205], v12 offset:9104
	ds_read_b128 v[206:209], v12 offset:17296
	s_waitcnt vmcnt(39) lgkmcnt(9)
	v_fmac_f32_e32 v6, v160, v210
	v_fmac_f32_e32 v7, v160, v214
	v_fmac_f32_e32 v11, v160, v218
	s_waitcnt vmcnt(38)
	v_fmac_f32_e32 v6, v161, v211
	v_fmac_f32_e32 v7, v161, v215
	v_fmac_f32_e32 v11, v161, v219
	s_waitcnt vmcnt(37)
	v_fmac_f32_e32 v6, v162, v212
	v_fmac_f32_e32 v7, v162, v216
	v_fmac_f32_e32 v11, v162, v220
	s_waitcnt vmcnt(36)
	v_fmac_f32_e32 v6, v163, v213
	v_fmac_f32_e32 v7, v163, v217
	v_fmac_f32_e32 v11, v163, v221
	ds_read_b128 v[210:213], v12 offset:928
	ds_read_b128 v[214:217], v12 offset:9120
	ds_read_b128 v[218:221], v12 offset:17312
	s_waitcnt vmcnt(35) lgkmcnt(9)
	v_fmac_f32_e32 v6, v164, v222
	v_fmac_f32_e32 v7, v164, v226
	v_fmac_f32_e32 v11, v164, v230
	s_waitcnt vmcnt(34)
	v_fmac_f32_e32 v6, v165, v223
	v_fmac_f32_e32 v7, v165, v227
	v_fmac_f32_e32 v11, v165, v231
	s_waitcnt vmcnt(33)
	v_fmac_f32_e32 v6, v166, v224
	v_fmac_f32_e32 v7, v166, v228
	v_fmac_f32_e32 v11, v166, v232
	s_waitcnt vmcnt(32)
	v_fmac_f32_e32 v6, v167, v225
	v_fmac_f32_e32 v7, v167, v229
	v_fmac_f32_e32 v11, v167, v233
	ds_read_b128 v[222:225], v12 offset:944
	ds_read_b128 v[226:229], v12 offset:9136
	ds_read_b128 v[230:233], v12 offset:17328
	s_waitcnt vmcnt(31) lgkmcnt(9)
	v_fmac_f32_e32 v6, v168, v186
	v_fmac_f32_e32 v7, v168, v190
	v_fmac_f32_e32 v11, v168, v194
	s_waitcnt vmcnt(30)
	v_fmac_f32_e32 v6, v169, v187
	v_fmac_f32_e32 v7, v169, v191
	v_fmac_f32_e32 v11, v169, v195
	s_waitcnt vmcnt(29)
	v_fmac_f32_e32 v6, v170, v188
	v_fmac_f32_e32 v7, v170, v192
	v_fmac_f32_e32 v11, v170, v196
	s_waitcnt vmcnt(28)
	v_fmac_f32_e32 v6, v171, v189
	v_fmac_f32_e32 v7, v171, v193
	v_fmac_f32_e32 v11, v171, v197
	ds_read_b128 v[186:189], v12 offset:960
	ds_read_b128 v[190:193], v12 offset:9152
	ds_read_b128 v[194:197], v12 offset:17344
	s_waitcnt vmcnt(27) lgkmcnt(9)
; __device__ __forceinline__ void mod_item(PREF P, int l, int nt, float* sm) {
;     ...
;     for (int k = kg * 256; k < kg * 256 + 256; ++k) { const float wv = w[(size_t)k * 6144]; a0 += sc[k] * wv; a1 += sc[2048 + k] * wv; a2 += sc[4096 + k] * wv; }
;     red[(kg * 3 + 0) * 64 + col] = a0; red[(kg * 3 + 1) * 64 + col] = a1; red[(kg * 3 + 2) * 64 + col] = a2;
;     __syncthreads();
;     if (tid < 192) { const int r = tid >> 6, c = tid & 63; float s = 0.f;
; #pragma unroll
;         for (int k = 0; k < 8; ++k) s += red[(k * 3 + r) * 64 + c];
;         float* MOD = (float*)(P.ws + l * SZ_LAYER + LO_MOD); MOD[r * 6144 + nt * 64 + c] = s + P.b_ada[l * 6144 + nt * 64 + c]; }
	v_fmac_f32_e32 v6, v172, v198
	v_fmac_f32_e32 v7, v172, v202
	v_fmac_f32_e32 v11, v172, v206
	s_waitcnt vmcnt(26)
	v_fmac_f32_e32 v6, v173, v199
	v_fmac_f32_e32 v7, v173, v203
	v_fmac_f32_e32 v11, v173, v207
	s_waitcnt vmcnt(25)
	v_fmac_f32_e32 v6, v174, v200
	v_fmac_f32_e32 v7, v174, v204
	v_fmac_f32_e32 v11, v174, v208
	s_waitcnt vmcnt(24)
	v_fmac_f32_e32 v6, v175, v201
	v_fmac_f32_e32 v7, v175, v205
	v_fmac_f32_e32 v11, v175, v209
	ds_read_b128 v[198:201], v12 offset:976
	ds_read_b128 v[202:205], v12 offset:9168
	ds_read_b128 v[206:209], v12 offset:17360
	s_waitcnt vmcnt(23) lgkmcnt(9)
	v_fmac_f32_e32 v6, v176, v210
	v_fmac_f32_e32 v7, v176, v214
	v_fmac_f32_e32 v11, v176, v218
	s_waitcnt vmcnt(22)
	v_fmac_f32_e32 v6, v177, v211
	v_fmac_f32_e32 v7, v177, v215
	v_fmac_f32_e32 v11, v177, v219
	s_waitcnt vmcnt(21)
	v_fmac_f32_e32 v6, v178, v212
	v_fmac_f32_e32 v7, v178, v216
	v_fmac_f32_e32 v11, v178, v220
	s_waitcnt vmcnt(20)
	v_fmac_f32_e32 v6, v179, v213
	v_fmac_f32_e32 v7, v179, v217
	v_fmac_f32_e32 v11, v179, v221
	ds_read_b128 v[210:213], v12 offset:992
	ds_read_b128 v[214:217], v12 offset:9184
	ds_read_b128 v[218:221], v12 offset:17376
	s_waitcnt vmcnt(19) lgkmcnt(9)
	v_fmac_f32_e32 v6, v180, v222
	v_fmac_f32_e32 v7, v180, v226
	v_fmac_f32_e32 v11, v180, v230
	s_waitcnt vmcnt(18)
	v_fmac_f32_e32 v6, v181, v223
	v_fmac_f32_e32 v7, v181, v227
	v_fmac_f32_e32 v11, v181, v231
	s_waitcnt vmcnt(17)
	v_fmac_f32_e32 v6, v182, v224
	v_fmac_f32_e32 v7, v182, v228
	v_fmac_f32_e32 v11, v182, v232
	s_waitcnt vmcnt(16)
	v_fmac_f32_e32 v6, v183, v225
	v_fmac_f32_e32 v7, v183, v229
	v_fmac_f32_e32 v11, v183, v233
	ds_read_b128 v[222:225], v12 offset:1008
	ds_read_b128 v[226:229], v12 offset:9200
	ds_read_b128 v[230:233], v12 offset:17392
	s_waitcnt vmcnt(15) lgkmcnt(9)
	v_fmac_f32_e32 v6, v124, v186
	v_fmac_f32_e32 v7, v124, v190
	v_fmac_f32_e32 v11, v124, v194
	s_waitcnt vmcnt(14)
	v_fmac_f32_e32 v6, v125, v187
	v_fmac_f32_e32 v7, v125, v191
	v_fmac_f32_e32 v11, v125, v195
	s_waitcnt vmcnt(13)
	v_fmac_f32_e32 v6, v126, v188
	v_fmac_f32_e32 v7, v126, v192
	v_fmac_f32_e32 v11, v126, v196
	s_waitcnt vmcnt(12)
	v_fmac_f32_e32 v6, v127, v189
	v_fmac_f32_e32 v7, v127, v193
	v_fmac_f32_e32 v11, v127, v197
	s_waitcnt vmcnt(11) lgkmcnt(6)
	v_fmac_f32_e32 v6, v128, v198
	v_fmac_f32_e32 v7, v128, v202
	v_fmac_f32_e32 v11, v128, v206
	s_waitcnt vmcnt(10)
	v_fmac_f32_e32 v6, v129, v199
	v_fmac_f32_e32 v7, v129, v203
	v_fmac_f32_e32 v11, v129, v207
	s_waitcnt vmcnt(9)
	v_fmac_f32_e32 v6, v130, v200
	v_fmac_f32_e32 v7, v130, v204
	v_fmac_f32_e32 v11, v130, v208
	s_waitcnt vmcnt(8)
	v_fmac_f32_e32 v6, v131, v201
	v_fmac_f32_e32 v7, v131, v205
	v_fmac_f32_e32 v11, v131, v209
	s_waitcnt vmcnt(7) lgkmcnt(3)
	v_fmac_f32_e32 v6, v132, v210
	v_fmac_f32_e32 v7, v132, v214
	v_fmac_f32_e32 v11, v132, v218
	s_waitcnt vmcnt(6)
	v_fmac_f32_e32 v6, v133, v211
	v_fmac_f32_e32 v7, v133, v215
	v_fmac_f32_e32 v11, v133, v219
	s_waitcnt vmcnt(5)
	v_fmac_f32_e32 v6, v134, v212
	v_fmac_f32_e32 v7, v134, v216
	v_fmac_f32_e32 v11, v134, v220
	s_waitcnt vmcnt(4)
	v_fmac_f32_e32 v6, v135, v213
	v_fmac_f32_e32 v7, v135, v217
	v_fmac_f32_e32 v11, v135, v221
	s_waitcnt vmcnt(3) lgkmcnt(0)
	v_fmac_f32_e32 v6, v136, v222
	v_fmac_f32_e32 v7, v136, v226
	v_fmac_f32_e32 v11, v136, v230
	s_waitcnt vmcnt(2)
	v_fmac_f32_e32 v6, v137, v223
	v_fmac_f32_e32 v7, v137, v227
	v_fmac_f32_e32 v11, v137, v231
	s_waitcnt vmcnt(1)
	v_fmac_f32_e32 v6, v138, v224
	v_fmac_f32_e32 v7, v138, v228
	v_fmac_f32_e32 v11, v138, v232
	s_waitcnt vmcnt(0)
	v_fmac_f32_e32 v6, v139, v225
	v_fmac_f32_e32 v7, v139, v229
	v_fmac_f32_e32 v11, v139, v233
	v_add_u32_e32 v12, 0x400, v12
	s_mov_b32 s9, 0xc000
	s_mov_b32 s51, 0x12000
	s_mov_b32 s52, 0x18000
	s_mov_b32 s53, 0x1e000
	s_mov_b32 s54, 0x24000
	s_mov_b32 s55, 0x2a000
	s_mov_b32 s56, 0x30000
	s_mov_b32 s57, 0x36000
	s_mov_b32 s58, 0x3c000
	s_mov_b32 s62, 0x42000
	s_mov_b32 s63, 0x48000
	s_mov_b32 s66, 0x4e000
	s_mov_b32 s67, 0x54000
	s_mov_b32 s68, 0x5a000
	s_mov_b32 s46, 0x600000
	s_mov_b32 s47, 0
	s_cmp_eq_u32 s46, 0x600000
	s_movk_i32 s9, 0x300
	v_mul_lo_u32 v5, v3, s9
	v_lshlrev_b32_e32 v4, 2, v1
	s_movk_i32 s9, 0xc0
	v_add3_u32 v5, 16, v5, v4
	v_cmp_gt_i32_e32 vcc, s9, v2
	ds_write2st64_b32 v5, v6, v7 offset0:96 offset1:97
	ds_write_b32 v5, v11 offset:25088
	s_waitcnt lgkmcnt(0)
	s_barrier
	s_and_saveexec_b64 s[46:47], vcc
	s_cbranch_execz .LBB0_103
	s_and_b64 s[52:53], s[44:45], exec
	s_cselect_b32 s9, 0x6e22000, 0
	s_add_u32 s52, s34, s9
	s_addc_u32 s53, s35, 0
	s_load_dwordx2 s[54:55], s[6:7], 0x28
	s_and_b64 s[44:45], s[44:45], exec
	s_cselect_b32 s9, 0x1800, 0
	s_add_i32 s9, s86, s9
	v_or_b32_e32 v22, s9, v1
	s_waitcnt lgkmcnt(0)
	v_lshl_add_u64 v[6:7], v[22:23], 2, s[54:55]
	global_load_dword v12, v[6:7], off
	v_add3_u32 v8, 16, v4, v10
	s_movk_i32 s9, 0x1800
	v_mul_lo_u32 v10, v3, s9
	ds_read2st64_b32 v[2:3], v8 offset0:96 offset1:99
	ds_read2st64_b32 v[4:5], v8 offset0:102 offset1:105
	ds_read2st64_b32 v[6:7], v8 offset0:108 offset1:111
	ds_read2st64_b32 v[8:9], v8 offset0:114 offset1:117
	v_add_u32_e32 v10, s86, v10
	v_or_b32_e32 v10, v10, v1
	s_waitcnt lgkmcnt(3)
	v_add_f32_e32 v1, 0, v2
	v_add_f32_e32 v1, v1, v3
	s_waitcnt lgkmcnt(2)
	v_add_f32_e32 v1, v1, v4
	v_add_f32_e32 v1, v1, v5
	s_waitcnt lgkmcnt(1)
	v_add_f32_e32 v1, v1, v6
	v_ashrrev_i32_e32 v11, 31, v10
	v_add_f32_e32 v1, v1, v7
	v_lshl_add_u64 v[10:11], v[10:11], 2, s[52:53]
	s_waitcnt lgkmcnt(0)
	v_add_f32_e32 v1, v1, v8
	v_add_co_u32_e32 v10, vcc, 0x6e10000, v10
	v_add_f32_e32 v1, v1, v9
	s_nop 0
	v_addc_co_u32_e32 v11, vcc, 0, v11, vcc
	s_waitcnt vmcnt(0)
	v_add_f32_e32 v1, v1, v12
	global_store_dword v[10:11], v1, off
